# P5/P8: next tile's SA11 stage issued before the epilogue stores; no vmcnt wait in a tile's first K-iteration depends on store acks except the last
# speedup vs baseline: 1.0036x; 1.0013x over previous
.LBB0_876:
	s_add_u32 s10, s22, 0x1c00000
	s_addc_u32 s11, s23, 0
	s_add_u32 s51, s22, 0x18ba4000
	v_readlane_b32 s31, v246, 0
	s_addc_u32 s52, s23, 0
	s_add_i32 s19, s31, 0x18000
	s_and_b32 s53, s9, 3
	s_add_i32 s54, s19, s5
	s_mov_b64 s[12:13], 0x80
	s_lshl_b32 s9, s4, 13
	s_lshl_b32 s18, s53, 12
	v_lshl_add_u64 v[6:7], v[6:7], 0, s[12:13]
	s_mov_b32 m0, s54
	s_add_i32 s55, s54, 0x2000
	s_add_i32 s56, s45, 0x8000
	s_add_i32 s57, s45, 0xa000
	global_load_lds_dwordx4 v[6:7], off
	v_lshl_add_u64 v[4:5], v[4:5], 0, s[12:13]
	s_mov_b32 m0, s55
	s_add_u32 s16, s28, 0x40080
	global_load_lds_dwordx4 v[4:5], off
	v_lshl_add_u64 v[2:3], v[2:3], 0, s[12:13]
	s_mov_b32 m0, s56
	s_addc_u32 s17, s29, 0
	s_add_i32 s25, s31, 0x1c000
	global_load_lds_dwordx4 v[2:3], off
	v_lshl_add_u64 v[0:1], v[0:1], 0, s[12:13]
	s_mov_b32 m0, s57
	s_add_i32 s58, s25, s5
	global_load_lds_dwordx4 v[0:1], off
	v_lshl_add_u64 v[0:1], s[16:17], 0, v[160:161]
	s_mov_b32 m0, s58
	s_add_i32 s59, s58, 0x2000
	global_load_lds_dwordx4 v[0:1], off
	v_lshl_add_u64 v[0:1], s[16:17], 0, v[162:163]
	s_mov_b32 m0, s59
	v_lshlrev_b32_e32 v5, 6, v202
	global_load_lds_dwordx4 v[0:1], off
	s_waitcnt vmcnt(8)
	s_barrier
	v_bfe_u32 v0, v202, 4, 2
	v_and_b32_e32 v1, 15, v202
	s_waitcnt vmcnt(0)
	v_lshl_or_b32 v184, s4, 6, v1
	v_lshlrev_b32_e32 v3, 4, v0
	s_movk_i32 s4, 0x3c0
	v_lshlrev_b32_e32 v2, 3, v0
	v_lshl_or_b32 v1, v1, 6, v3
	v_and_or_b32 v3, v5, s4, v3
	v_cmp_eq_u32_e64 s[4:5], 0, v0
	v_lshlrev_b32_e32 v0, 8, v202
	v_lshl_or_b32 v185, s53, 6, v2
	v_and_b32_e32 v0, 0xffff8000, v0
	v_lshlrev_b32_e32 v2, 11, v10
	v_or3_b32 v0, v8, v0, v2
	v_add_u32_e32 v164, v0, v9
	v_lshlrev_b32_e32 v0, 4, v11
	v_lshlrev_b32_e32 v4, 2, v202
	v_and_b32_e32 v0, 0xffff8000, v0
	v_and_b32_e32 v4, 32, v4
	s_waitcnt vmcnt(6)
	v_or3_b32 v0, v8, v0, v2
	v_bitop3_b32 v1, v1, s9, v4 bitop3:0xde
	v_bitop3_b32 v3, s18, v3, v4 bitop3:0xf6
	s_mov_b32 s9, 0
	v_readlane_b32 s16, v246, 1
	v_add_u32_e32 v166, v0, v9
	v_mbcnt_lo_u32_b32 v0, -1, 0
	v_readlane_b32 s17, v246, 2
	s_ashr_i32 s60, s16, 31
	s_mov_b32 s61, s16
	s_ashr_i32 s62, s30, 31
	s_lshr_b32 s63, s33, 1
	v_mov_b32_e32 v165, v161
	v_mov_b32_e32 v167, v161
	v_mov_b64_e32 v[168:169], s[8:9]
	v_add_u32_e32 v186, s14, v3
	v_add_u32_e32 v187, s31, v1
	v_add_u32_e32 v188, s15, v3
	v_add_u32_e32 v189, s19, v3
	v_add_u32_e32 v190, s25, v3
	v_mbcnt_hi_u32_b32 v191, -1, v0
	s_barrier
	s_add_u32 s80, s26, 0x40080
	s_addc_u32 s81, s27, 0
	v_lshl_add_u64 v[182:183], s[80:81], 0, v[164:165]
	s_add_i32 m0, s45, 0xc000
	s_nop 0
	global_load_lds_dwordx4 v[182:183], off
	v_lshl_add_u64 v[182:183], s[80:81], 0, v[166:167]
	s_add_i32 m0, s45, 0xe000
	s_nop 0
	global_load_lds_dwordx4 v[182:183], off
	s_waitcnt vmcnt(0)
	s_branch .LBB0_878

.LBB0_882:
	s_xor_b64 s[18:19], s[36:37], -1
	s_and_b64 s[30:31], s[36:37], exec
	s_cselect_b32 s25, s15, s27
	s_cselect_b32 s34, s14, s26
	s_cselect_b32 s36, s17, s29
	s_cselect_b32 s37, s16, s28
	s_add_u32 s26, s26, 0x40080
	s_addc_u32 s27, s27, 0
	s_add_u32 s38, s28, 0x100
	s_addc_u32 s39, s29, 0
	s_mov_b32 s40, -2
	s_waitcnt lgkmcnt(0)
	ds_read_b128 v[128:131], v186
	ds_read_b128 v[132:135], v186 offset:1024
	ds_read_b128 v[136:139], v186 offset:2048
	ds_read_b128 v[140:143], v186 offset:3072
	s_add_u32 s28, s26, 0xfffc0080
	s_addc_u32 s29, s27, -1
	s_cmp_eq_u32 s40, 12
	s_cselect_b32 s31, s25, s29
	s_cselect_b32 s30, s34, s28
	s_cselect_b32 s29, s36, s39
	s_cselect_b32 s28, s37, s38
	ds_read_b128 v[144:147], v187
	ds_read_b128 v[148:151], v187 offset:1024
	ds_read_b128 v[152:155], v187 offset:2048
	ds_read_b128 v[156:159], v187 offset:3072
	ds_read_b128 v[170:173], v187 offset:4096
	ds_read_b128 v[174:177], v187 offset:5120
	ds_read_b128 v[178:181], v187 offset:6144
	ds_read_b128 v[192:195], v187 offset:7168
	ds_read_b128 v[196:199], v188
	ds_read_b128 v[204:207], v188 offset:1024
	ds_read_b128 v[208:211], v188 offset:2048
	ds_read_b128 v[212:215], v188 offset:3072
	s_waitcnt lgkmcnt(0)
	s_nop 0
	s_barrier
	s_setprio 1
	v_mfma_f32_16x16x32_bf16 v[124:127], v[128:131], v[144:147], 0
	v_mfma_f32_16x16x32_bf16 v[120:123], v[136:139], v[144:147], 0
	v_mfma_f32_16x16x32_bf16 v[108:111], v[128:131], v[152:155], 0
	v_mfma_f32_16x16x32_bf16 v[104:107], v[136:139], v[152:155], 0
	v_mfma_f32_16x16x32_bf16 v[92:95], v[128:131], v[170:173], 0
	v_mfma_f32_16x16x32_bf16 v[88:91], v[136:139], v[170:173], 0
	v_mfma_f32_16x16x32_bf16 v[76:79], v[128:131], v[178:181], 0
	v_mfma_f32_16x16x32_bf16 v[72:75], v[136:139], v[178:181], 0
	v_mfma_f32_16x16x32_bf16 v[124:127], v[132:135], v[148:151], v[124:127]
	v_mfma_f32_16x16x32_bf16 v[120:123], v[140:143], v[148:151], v[120:123]
	v_mfma_f32_16x16x32_bf16 v[108:111], v[132:135], v[156:159], v[108:111]
	v_mfma_f32_16x16x32_bf16 v[104:107], v[140:143], v[156:159], v[104:107]
	v_mfma_f32_16x16x32_bf16 v[92:95], v[132:135], v[174:177], v[92:95]
	v_mfma_f32_16x16x32_bf16 v[88:91], v[140:143], v[174:177], v[88:91]
	v_mfma_f32_16x16x32_bf16 v[76:79], v[132:135], v[192:195], v[76:79]
	v_mfma_f32_16x16x32_bf16 v[72:75], v[140:143], v[192:195], v[72:75]
	v_mfma_f32_16x16x32_bf16 v[116:119], v[196:199], v[144:147], 0
	v_mfma_f32_16x16x32_bf16 v[112:115], v[208:211], v[144:147], 0
	v_mfma_f32_16x16x32_bf16 v[100:103], v[196:199], v[152:155], 0
	v_mfma_f32_16x16x32_bf16 v[96:99], v[208:211], v[152:155], 0
	v_mfma_f32_16x16x32_bf16 v[84:87], v[196:199], v[170:173], 0
	v_mfma_f32_16x16x32_bf16 v[80:83], v[208:211], v[170:173], 0
	v_mfma_f32_16x16x32_bf16 v[68:71], v[196:199], v[178:181], 0
	v_mfma_f32_16x16x32_bf16 v[64:67], v[208:211], v[178:181], 0
	v_mfma_f32_16x16x32_bf16 v[116:119], v[204:207], v[148:151], v[116:119]
	v_mfma_f32_16x16x32_bf16 v[112:115], v[212:215], v[148:151], v[112:115]
	v_mfma_f32_16x16x32_bf16 v[100:103], v[204:207], v[156:159], v[100:103]
	v_mfma_f32_16x16x32_bf16 v[96:99], v[212:215], v[156:159], v[96:99]
	v_mfma_f32_16x16x32_bf16 v[84:87], v[204:207], v[174:177], v[84:87]
	v_mfma_f32_16x16x32_bf16 v[80:83], v[212:215], v[174:177], v[80:83]
	v_mfma_f32_16x16x32_bf16 v[68:71], v[204:207], v[192:195], v[68:71]
	v_mfma_f32_16x16x32_bf16 v[64:67], v[212:215], v[192:195], v[64:67]
	s_setprio 0
	s_barrier
	v_lshl_or_b32 v203, s65, 8, v185
	v_lshlrev_b32_e32 v203, 1, v203
	v_lshl_add_u32 v247, s24, 8, v184
	v_lshl_add_u32 v203, v247, 11, v203
	s_add_u32 s74, s10, 0x8000
	s_addc_u32 s75, s11, 0
	s_add_u32 s76, s10, 0x10000
	s_addc_u32 s77, s11, 0
	s_add_u32 s78, s10, 0x18000
	s_addc_u32 s79, s11, 0
	global_load_dwordx4 v[220:223], v203, s[10:11]
	global_load_dwordx4 v[224:227], v203, s[10:11] offset:64
	global_load_dwordx4 v[228:231], v203, s[74:75]
	global_load_dwordx4 v[232:235], v203, s[74:75] offset:64
	global_load_dwordx4 v[236:239], v203, s[76:77]
	global_load_dwordx4 v[240:243], v203, s[76:77] offset:64
	global_load_dwordx4 v[252:255], v203, s[78:79]
	ds_read_b128 v[144:147], v187 offset:16384
	ds_read_b128 v[148:151], v187 offset:17408
	ds_read_b128 v[152:155], v187 offset:18432
	ds_read_b128 v[156:159], v187 offset:19456
	ds_read_b128 v[170:173], v187 offset:20480
	ds_read_b128 v[174:177], v187 offset:21504
	ds_read_b128 v[178:181], v187 offset:22528
	ds_read_b128 v[192:195], v187 offset:23552
	s_mov_b32 m0, s43
	v_lshl_add_u64 v[182:183], s[28:29], 0, v[160:161]
	global_load_lds_dwordx4 v[182:183], off
	v_lshl_add_u64 v[200:201], s[28:29], 0, v[162:163]
	s_mov_b32 m0, s44
	s_nop 0
	global_load_lds_dwordx4 v[200:201], off
	s_mov_b32 m0, s45
	v_lshl_add_u64 v[216:217], s[30:31], 0, v[160:161]
	global_load_lds_dwordx4 v[216:217], off
	v_lshl_add_u64 v[218:219], s[30:31], 0, v[162:163]
	s_mov_b32 m0, s46
	s_nop 0
	global_load_lds_dwordx4 v[218:219], off
	s_add_u32 s66, s28, 0x40000
	s_addc_u32 s67, s29, 0
	s_mov_b32 m0, s47
	v_lshl_add_u64 v[248:249], s[66:67], 0, v[160:161]
	global_load_lds_dwordx4 v[248:249], off
	v_lshl_add_u64 v[248:249], s[66:67], 0, v[162:163]
	s_mov_b32 m0, s48
	s_nop 0
	global_load_lds_dwordx4 v[248:249], off
	s_waitcnt lgkmcnt(0)
	s_nop 0
	s_barrier
	s_setprio 1
	v_mfma_f32_16x16x32_bf16 v[60:63], v[128:131], v[144:147], 0
	v_mfma_f32_16x16x32_bf16 v[56:59], v[136:139], v[144:147], 0
	v_mfma_f32_16x16x32_bf16 v[44:47], v[128:131], v[152:155], 0
	v_mfma_f32_16x16x32_bf16 v[40:43], v[136:139], v[152:155], 0
	v_mfma_f32_16x16x32_bf16 v[28:31], v[128:131], v[170:173], 0
	v_mfma_f32_16x16x32_bf16 v[24:27], v[136:139], v[170:173], 0
	v_mfma_f32_16x16x32_bf16 v[12:15], v[128:131], v[178:181], 0
	v_mfma_f32_16x16x32_bf16 v[8:11], v[136:139], v[178:181], 0
	v_mfma_f32_16x16x32_bf16 v[60:63], v[132:135], v[148:151], v[60:63]
	v_mfma_f32_16x16x32_bf16 v[56:59], v[140:143], v[148:151], v[56:59]
	v_mfma_f32_16x16x32_bf16 v[44:47], v[132:135], v[156:159], v[44:47]
	v_mfma_f32_16x16x32_bf16 v[40:43], v[140:143], v[156:159], v[40:43]
	v_mfma_f32_16x16x32_bf16 v[28:31], v[132:135], v[174:177], v[28:31]
	v_mfma_f32_16x16x32_bf16 v[24:27], v[140:143], v[174:177], v[24:27]
	v_mfma_f32_16x16x32_bf16 v[12:15], v[132:135], v[192:195], v[12:15]
	v_mfma_f32_16x16x32_bf16 v[8:11], v[140:143], v[192:195], v[8:11]
	v_mfma_f32_16x16x32_bf16 v[52:55], v[196:199], v[144:147], 0
	v_mfma_f32_16x16x32_bf16 v[48:51], v[208:211], v[144:147], 0
	v_mfma_f32_16x16x32_bf16 v[36:39], v[196:199], v[152:155], 0
	v_mfma_f32_16x16x32_bf16 v[32:35], v[208:211], v[152:155], 0
	v_mfma_f32_16x16x32_bf16 v[20:23], v[196:199], v[170:173], 0
	v_mfma_f32_16x16x32_bf16 v[16:19], v[208:211], v[170:173], 0
	v_mfma_f32_16x16x32_bf16 v[4:7], v[196:199], v[178:181], 0
	v_mfma_f32_16x16x32_bf16 v[0:3], v[208:211], v[178:181], 0
	v_mfma_f32_16x16x32_bf16 v[52:55], v[204:207], v[148:151], v[52:55]
	v_mfma_f32_16x16x32_bf16 v[48:51], v[212:215], v[148:151], v[48:51]
	v_mfma_f32_16x16x32_bf16 v[36:39], v[204:207], v[156:159], v[36:39]
	v_mfma_f32_16x16x32_bf16 v[32:35], v[212:215], v[156:159], v[32:35]
	v_mfma_f32_16x16x32_bf16 v[20:23], v[204:207], v[174:177], v[20:23]
	v_mfma_f32_16x16x32_bf16 v[16:19], v[212:215], v[174:177], v[16:19]
	v_mfma_f32_16x16x32_bf16 v[4:7], v[204:207], v[192:195], v[4:7]
	v_mfma_f32_16x16x32_bf16 v[0:3], v[212:215], v[192:195], v[0:3]
	s_setprio 0
	s_barrier
	ds_read_b128 v[128:131], v189
	ds_read_b128 v[132:135], v189 offset:1024
	ds_read_b128 v[136:139], v189 offset:2048
	ds_read_b128 v[140:143], v189 offset:3072
	s_add_u32 s30, s30, 0x40000
	s_addc_u32 s31, s31, 0
	s_mov_b32 m0, s49
	v_lshl_add_u64 v[196:197], s[30:31], 0, v[160:161]
	ds_read_b128 v[144:147], v187 offset:32768
	ds_read_b128 v[148:151], v187 offset:33792
	ds_read_b128 v[152:155], v187 offset:34816
	ds_read_b128 v[156:159], v187 offset:35840
	ds_read_b128 v[170:173], v187 offset:36864
	ds_read_b128 v[174:177], v187 offset:37888
	ds_read_b128 v[178:181], v187 offset:38912
	ds_read_b128 v[192:195], v187 offset:39936
	global_load_lds_dwordx4 v[196:197], off
	v_lshl_add_u64 v[196:197], s[30:31], 0, v[162:163]
	s_mov_b32 m0, s50
	s_nop 0
	global_load_lds_dwordx4 v[196:197], off
	ds_read_b128 v[196:199], v190
	ds_read_b128 v[204:207], v190 offset:1024
	ds_read_b128 v[208:211], v190 offset:2048
	ds_read_b128 v[212:215], v190 offset:3072
	s_waitcnt lgkmcnt(0)
	s_nop 0
	s_barrier
	s_setprio 1
	v_mfma_f32_16x16x32_bf16 v[124:127], v[128:131], v[144:147], v[124:127]
	v_mfma_f32_16x16x32_bf16 v[120:123], v[136:139], v[144:147], v[120:123]
	v_mfma_f32_16x16x32_bf16 v[108:111], v[128:131], v[152:155], v[108:111]
	v_mfma_f32_16x16x32_bf16 v[104:107], v[136:139], v[152:155], v[104:107]
	v_mfma_f32_16x16x32_bf16 v[92:95], v[128:131], v[170:173], v[92:95]
	v_mfma_f32_16x16x32_bf16 v[88:91], v[136:139], v[170:173], v[88:91]
	v_mfma_f32_16x16x32_bf16 v[76:79], v[128:131], v[178:181], v[76:79]
	v_mfma_f32_16x16x32_bf16 v[72:75], v[136:139], v[178:181], v[72:75]
	v_mfma_f32_16x16x32_bf16 v[124:127], v[132:135], v[148:151], v[124:127]
	v_mfma_f32_16x16x32_bf16 v[120:123], v[140:143], v[148:151], v[120:123]
	v_mfma_f32_16x16x32_bf16 v[108:111], v[132:135], v[156:159], v[108:111]
	v_mfma_f32_16x16x32_bf16 v[104:107], v[140:143], v[156:159], v[104:107]
	v_mfma_f32_16x16x32_bf16 v[92:95], v[132:135], v[174:177], v[92:95]
	v_mfma_f32_16x16x32_bf16 v[88:91], v[140:143], v[174:177], v[88:91]
	v_mfma_f32_16x16x32_bf16 v[76:79], v[132:135], v[192:195], v[76:79]
	v_mfma_f32_16x16x32_bf16 v[72:75], v[140:143], v[192:195], v[72:75]
	v_mfma_f32_16x16x32_bf16 v[116:119], v[196:199], v[144:147], v[116:119]
	v_mfma_f32_16x16x32_bf16 v[112:115], v[208:211], v[144:147], v[112:115]
	v_mfma_f32_16x16x32_bf16 v[100:103], v[196:199], v[152:155], v[100:103]
	v_mfma_f32_16x16x32_bf16 v[96:99], v[208:211], v[152:155], v[96:99]
	v_mfma_f32_16x16x32_bf16 v[84:87], v[196:199], v[170:173], v[84:87]
	v_mfma_f32_16x16x32_bf16 v[80:83], v[208:211], v[170:173], v[80:83]
	v_mfma_f32_16x16x32_bf16 v[68:71], v[196:199], v[178:181], v[68:71]
	v_mfma_f32_16x16x32_bf16 v[64:67], v[208:211], v[178:181], v[64:67]
	v_mfma_f32_16x16x32_bf16 v[116:119], v[204:207], v[148:151], v[116:119]
	v_mfma_f32_16x16x32_bf16 v[112:115], v[212:215], v[148:151], v[112:115]
	v_mfma_f32_16x16x32_bf16 v[100:103], v[204:207], v[156:159], v[100:103]
	v_mfma_f32_16x16x32_bf16 v[96:99], v[212:215], v[156:159], v[96:99]
	v_mfma_f32_16x16x32_bf16 v[84:87], v[204:207], v[174:177], v[84:87]
	v_mfma_f32_16x16x32_bf16 v[80:83], v[212:215], v[174:177], v[80:83]
	v_mfma_f32_16x16x32_bf16 v[68:71], v[204:207], v[192:195], v[68:71]
	v_mfma_f32_16x16x32_bf16 v[64:67], v[212:215], v[192:195], v[64:67]
	s_setprio 0
	s_barrier
	ds_read_b128 v[144:147], v187 offset:49152
	ds_read_b128 v[148:151], v187 offset:50176
	ds_read_b128 v[152:155], v187 offset:51200
	ds_read_b128 v[156:159], v187 offset:52224
	ds_read_b128 v[170:173], v187 offset:53248
	ds_read_b128 v[174:177], v187 offset:54272
	ds_read_b128 v[178:181], v187 offset:55296
	ds_read_b128 v[192:195], v187 offset:56320
	s_mov_b32 m0, s54
	v_lshl_add_u64 v[182:183], v[182:183], 0, s[12:13]
	global_load_lds_dwordx4 v[182:183], off
	v_lshl_add_u64 v[182:183], v[200:201], 0, s[12:13]
	s_mov_b32 m0, s55
	s_nop 0
	global_load_lds_dwordx4 v[182:183], off
	s_mov_b32 m0, s56
	v_lshl_add_u64 v[182:183], v[216:217], 0, s[12:13]
	global_load_lds_dwordx4 v[182:183], off
	v_lshl_add_u64 v[182:183], v[218:219], 0, s[12:13]
	s_mov_b32 m0, s57
	s_nop 0
	global_load_lds_dwordx4 v[182:183], off
	s_add_u32 s28, s28, 0x40080
	s_addc_u32 s29, s29, 0
	s_mov_b32 m0, s58
	v_lshl_add_u64 v[248:249], s[28:29], 0, v[160:161]
	global_load_lds_dwordx4 v[248:249], off
	v_lshl_add_u64 v[248:249], s[28:29], 0, v[162:163]
	s_mov_b32 m0, s59
	s_nop 0
	global_load_lds_dwordx4 v[248:249], off
	s_waitcnt lgkmcnt(0)
	s_waitcnt vmcnt(8)
	s_barrier
	s_setprio 1
	v_mfma_f32_16x16x32_bf16 v[60:63], v[128:131], v[144:147], v[60:63]
	v_mfma_f32_16x16x32_bf16 v[56:59], v[136:139], v[144:147], v[56:59]
	v_mfma_f32_16x16x32_bf16 v[44:47], v[128:131], v[152:155], v[44:47]
	v_mfma_f32_16x16x32_bf16 v[40:43], v[136:139], v[152:155], v[40:43]
	v_mfma_f32_16x16x32_bf16 v[28:31], v[128:131], v[170:173], v[28:31]
	v_mfma_f32_16x16x32_bf16 v[24:27], v[136:139], v[170:173], v[24:27]
	v_mfma_f32_16x16x32_bf16 v[12:15], v[128:131], v[178:181], v[12:15]
	v_mfma_f32_16x16x32_bf16 v[8:11], v[136:139], v[178:181], v[8:11]
	v_mfma_f32_16x16x32_bf16 v[60:63], v[132:135], v[148:151], v[60:63]
	v_mfma_f32_16x16x32_bf16 v[56:59], v[140:143], v[148:151], v[56:59]
	v_mfma_f32_16x16x32_bf16 v[44:47], v[132:135], v[156:159], v[44:47]
	v_mfma_f32_16x16x32_bf16 v[40:43], v[140:143], v[156:159], v[40:43]
	v_mfma_f32_16x16x32_bf16 v[28:31], v[132:135], v[174:177], v[28:31]
	v_mfma_f32_16x16x32_bf16 v[24:27], v[140:143], v[174:177], v[24:27]
	v_mfma_f32_16x16x32_bf16 v[12:15], v[132:135], v[192:195], v[12:15]
	v_mfma_f32_16x16x32_bf16 v[8:11], v[140:143], v[192:195], v[8:11]
	v_mfma_f32_16x16x32_bf16 v[52:55], v[196:199], v[144:147], v[52:55]
	v_mfma_f32_16x16x32_bf16 v[48:51], v[208:211], v[144:147], v[48:51]
	v_mfma_f32_16x16x32_bf16 v[36:39], v[196:199], v[152:155], v[36:39]
	v_mfma_f32_16x16x32_bf16 v[32:35], v[208:211], v[152:155], v[32:35]
	v_mfma_f32_16x16x32_bf16 v[20:23], v[196:199], v[170:173], v[20:23]
	v_mfma_f32_16x16x32_bf16 v[16:19], v[208:211], v[170:173], v[16:19]
	v_mfma_f32_16x16x32_bf16 v[4:7], v[196:199], v[178:181], v[4:7]
	v_mfma_f32_16x16x32_bf16 v[0:3], v[208:211], v[178:181], v[0:3]
	v_mfma_f32_16x16x32_bf16 v[52:55], v[204:207], v[148:151], v[52:55]
	v_mfma_f32_16x16x32_bf16 v[48:51], v[212:215], v[148:151], v[48:51]
	v_mfma_f32_16x16x32_bf16 v[36:39], v[204:207], v[156:159], v[36:39]
	v_mfma_f32_16x16x32_bf16 v[32:35], v[212:215], v[156:159], v[32:35]
	v_mfma_f32_16x16x32_bf16 v[20:23], v[204:207], v[174:177], v[20:23]
	v_mfma_f32_16x16x32_bf16 v[16:19], v[212:215], v[174:177], v[16:19]
	v_mfma_f32_16x16x32_bf16 v[4:7], v[204:207], v[192:195], v[4:7]
	v_mfma_f32_16x16x32_bf16 v[0:3], v[212:215], v[192:195], v[0:3]
	s_setprio 0
	s_add_i32 s40, s40, 2
	s_add_u32 s26, s26, 0x100
	s_addc_u32 s27, s27, 0
	s_add_u32 s38, s38, 0x100
	s_addc_u32 s39, s39, 0
	s_cmp_gt_u32 s40, 13
	s_barrier
.LBB0_883:
	ds_read_b128 v[128:131], v186
	ds_read_b128 v[132:135], v186 offset:1024
	ds_read_b128 v[136:139], v186 offset:2048
	ds_read_b128 v[140:143], v186 offset:3072
	s_add_u32 s28, s26, 0xfffc0080
	s_addc_u32 s29, s27, -1
	s_cmp_eq_u32 s40, 12
	s_cselect_b32 s31, s25, s29
	s_cselect_b32 s30, s34, s28
	s_cselect_b32 s29, s36, s39
	s_cselect_b32 s28, s37, s38
	v_lshl_add_u64 v[182:183], s[26:27], 0, v[164:165]
	s_add_i32 m0, s45, 0xc000
	ds_read_b128 v[144:147], v187
	ds_read_b128 v[148:151], v187 offset:1024
	ds_read_b128 v[152:155], v187 offset:2048
	ds_read_b128 v[156:159], v187 offset:3072
	ds_read_b128 v[170:173], v187 offset:4096
	ds_read_b128 v[174:177], v187 offset:5120
	ds_read_b128 v[178:181], v187 offset:6144
	ds_read_b128 v[192:195], v187 offset:7168
	global_load_lds_dwordx4 v[182:183], off
	v_lshl_add_u64 v[182:183], s[26:27], 0, v[166:167]
	s_add_i32 m0, s45, 0xe000
	s_nop 0
	global_load_lds_dwordx4 v[182:183], off
	ds_read_b128 v[196:199], v188
	ds_read_b128 v[204:207], v188 offset:1024
	ds_read_b128 v[208:211], v188 offset:2048
	ds_read_b128 v[212:215], v188 offset:3072
	s_waitcnt lgkmcnt(0)
	s_waitcnt vmcnt(8)
	s_barrier
	s_setprio 1
	v_mfma_f32_16x16x32_bf16 v[124:127], v[128:131], v[144:147], v[124:127]
	v_mfma_f32_16x16x32_bf16 v[120:123], v[136:139], v[144:147], v[120:123]
	v_mfma_f32_16x16x32_bf16 v[108:111], v[128:131], v[152:155], v[108:111]
	v_mfma_f32_16x16x32_bf16 v[104:107], v[136:139], v[152:155], v[104:107]
	v_mfma_f32_16x16x32_bf16 v[92:95], v[128:131], v[170:173], v[92:95]
	v_mfma_f32_16x16x32_bf16 v[88:91], v[136:139], v[170:173], v[88:91]
	v_mfma_f32_16x16x32_bf16 v[76:79], v[128:131], v[178:181], v[76:79]
	v_mfma_f32_16x16x32_bf16 v[72:75], v[136:139], v[178:181], v[72:75]
	v_mfma_f32_16x16x32_bf16 v[124:127], v[132:135], v[148:151], v[124:127]
	v_mfma_f32_16x16x32_bf16 v[120:123], v[140:143], v[148:151], v[120:123]
	v_mfma_f32_16x16x32_bf16 v[108:111], v[132:135], v[156:159], v[108:111]
	v_mfma_f32_16x16x32_bf16 v[104:107], v[140:143], v[156:159], v[104:107]
	v_mfma_f32_16x16x32_bf16 v[92:95], v[132:135], v[174:177], v[92:95]
	v_mfma_f32_16x16x32_bf16 v[88:91], v[140:143], v[174:177], v[88:91]
	v_mfma_f32_16x16x32_bf16 v[76:79], v[132:135], v[192:195], v[76:79]
	v_mfma_f32_16x16x32_bf16 v[72:75], v[140:143], v[192:195], v[72:75]
	v_mfma_f32_16x16x32_bf16 v[116:119], v[196:199], v[144:147], v[116:119]
	v_mfma_f32_16x16x32_bf16 v[112:115], v[208:211], v[144:147], v[112:115]
	v_mfma_f32_16x16x32_bf16 v[100:103], v[196:199], v[152:155], v[100:103]
	v_mfma_f32_16x16x32_bf16 v[96:99], v[208:211], v[152:155], v[96:99]
	v_mfma_f32_16x16x32_bf16 v[84:87], v[196:199], v[170:173], v[84:87]
	v_mfma_f32_16x16x32_bf16 v[80:83], v[208:211], v[170:173], v[80:83]
	v_mfma_f32_16x16x32_bf16 v[68:71], v[196:199], v[178:181], v[68:71]
	v_mfma_f32_16x16x32_bf16 v[64:67], v[208:211], v[178:181], v[64:67]
	v_mfma_f32_16x16x32_bf16 v[116:119], v[204:207], v[148:151], v[116:119]
	v_mfma_f32_16x16x32_bf16 v[112:115], v[212:215], v[148:151], v[112:115]
	v_mfma_f32_16x16x32_bf16 v[100:103], v[204:207], v[156:159], v[100:103]
	v_mfma_f32_16x16x32_bf16 v[96:99], v[212:215], v[156:159], v[96:99]
	v_mfma_f32_16x16x32_bf16 v[84:87], v[204:207], v[174:177], v[84:87]
	v_mfma_f32_16x16x32_bf16 v[80:83], v[212:215], v[174:177], v[80:83]
	v_mfma_f32_16x16x32_bf16 v[68:71], v[204:207], v[192:195], v[68:71]
	v_mfma_f32_16x16x32_bf16 v[64:67], v[212:215], v[192:195], v[64:67]
	s_setprio 0
	s_barrier
	ds_read_b128 v[144:147], v187 offset:16384
	ds_read_b128 v[148:151], v187 offset:17408
	ds_read_b128 v[152:155], v187 offset:18432
	ds_read_b128 v[156:159], v187 offset:19456
	ds_read_b128 v[170:173], v187 offset:20480
	ds_read_b128 v[174:177], v187 offset:21504
	ds_read_b128 v[178:181], v187 offset:22528
	ds_read_b128 v[192:195], v187 offset:23552
	s_mov_b32 m0, s43
	v_lshl_add_u64 v[182:183], s[28:29], 0, v[160:161]
	global_load_lds_dwordx4 v[182:183], off
	v_lshl_add_u64 v[200:201], s[28:29], 0, v[162:163]
	s_mov_b32 m0, s44
	s_nop 0
	global_load_lds_dwordx4 v[200:201], off
	s_mov_b32 m0, s45
	v_lshl_add_u64 v[216:217], s[30:31], 0, v[160:161]
	global_load_lds_dwordx4 v[216:217], off
	v_lshl_add_u64 v[218:219], s[30:31], 0, v[162:163]
	s_mov_b32 m0, s46
	s_nop 0
	global_load_lds_dwordx4 v[218:219], off
	s_add_u32 s66, s28, 0x40000
	s_addc_u32 s67, s29, 0
	s_mov_b32 m0, s47
	v_lshl_add_u64 v[248:249], s[66:67], 0, v[160:161]
	global_load_lds_dwordx4 v[248:249], off
	v_lshl_add_u64 v[248:249], s[66:67], 0, v[162:163]
	s_mov_b32 m0, s48
	s_nop 0
	global_load_lds_dwordx4 v[248:249], off
	s_waitcnt lgkmcnt(0)
	s_waitcnt vmcnt(8)
	s_barrier
	s_setprio 1
	v_mfma_f32_16x16x32_bf16 v[60:63], v[128:131], v[144:147], v[60:63]
	v_mfma_f32_16x16x32_bf16 v[56:59], v[136:139], v[144:147], v[56:59]
	v_mfma_f32_16x16x32_bf16 v[44:47], v[128:131], v[152:155], v[44:47]
	v_mfma_f32_16x16x32_bf16 v[40:43], v[136:139], v[152:155], v[40:43]
	v_mfma_f32_16x16x32_bf16 v[28:31], v[128:131], v[170:173], v[28:31]
	v_mfma_f32_16x16x32_bf16 v[24:27], v[136:139], v[170:173], v[24:27]
	v_mfma_f32_16x16x32_bf16 v[12:15], v[128:131], v[178:181], v[12:15]
	v_mfma_f32_16x16x32_bf16 v[8:11], v[136:139], v[178:181], v[8:11]
	v_mfma_f32_16x16x32_bf16 v[60:63], v[132:135], v[148:151], v[60:63]
	v_mfma_f32_16x16x32_bf16 v[56:59], v[140:143], v[148:151], v[56:59]
	v_mfma_f32_16x16x32_bf16 v[44:47], v[132:135], v[156:159], v[44:47]
	v_mfma_f32_16x16x32_bf16 v[40:43], v[140:143], v[156:159], v[40:43]
	v_mfma_f32_16x16x32_bf16 v[28:31], v[132:135], v[174:177], v[28:31]
	v_mfma_f32_16x16x32_bf16 v[24:27], v[140:143], v[174:177], v[24:27]
	v_mfma_f32_16x16x32_bf16 v[12:15], v[132:135], v[192:195], v[12:15]
	v_mfma_f32_16x16x32_bf16 v[8:11], v[140:143], v[192:195], v[8:11]
	v_mfma_f32_16x16x32_bf16 v[52:55], v[196:199], v[144:147], v[52:55]
	v_mfma_f32_16x16x32_bf16 v[48:51], v[208:211], v[144:147], v[48:51]
	v_mfma_f32_16x16x32_bf16 v[36:39], v[196:199], v[152:155], v[36:39]
	v_mfma_f32_16x16x32_bf16 v[32:35], v[208:211], v[152:155], v[32:35]
	v_mfma_f32_16x16x32_bf16 v[20:23], v[196:199], v[170:173], v[20:23]
	v_mfma_f32_16x16x32_bf16 v[16:19], v[208:211], v[170:173], v[16:19]
	v_mfma_f32_16x16x32_bf16 v[4:7], v[196:199], v[178:181], v[4:7]
	v_mfma_f32_16x16x32_bf16 v[0:3], v[208:211], v[178:181], v[0:3]
	v_mfma_f32_16x16x32_bf16 v[52:55], v[204:207], v[148:151], v[52:55]
	v_mfma_f32_16x16x32_bf16 v[48:51], v[212:215], v[148:151], v[48:51]
	v_mfma_f32_16x16x32_bf16 v[36:39], v[204:207], v[156:159], v[36:39]
	v_mfma_f32_16x16x32_bf16 v[32:35], v[212:215], v[156:159], v[32:35]
	v_mfma_f32_16x16x32_bf16 v[20:23], v[204:207], v[174:177], v[20:23]
	v_mfma_f32_16x16x32_bf16 v[16:19], v[212:215], v[174:177], v[16:19]
	v_mfma_f32_16x16x32_bf16 v[4:7], v[204:207], v[192:195], v[4:7]
	v_mfma_f32_16x16x32_bf16 v[0:3], v[212:215], v[192:195], v[0:3]
	s_setprio 0
	s_barrier
	ds_read_b128 v[128:131], v189
	ds_read_b128 v[132:135], v189 offset:1024
	ds_read_b128 v[136:139], v189 offset:2048
	ds_read_b128 v[140:143], v189 offset:3072
	s_add_u32 s30, s30, 0x40000
	s_addc_u32 s31, s31, 0
	s_mov_b32 m0, s49
	v_lshl_add_u64 v[196:197], s[30:31], 0, v[160:161]
	ds_read_b128 v[144:147], v187 offset:32768
	ds_read_b128 v[148:151], v187 offset:33792
	ds_read_b128 v[152:155], v187 offset:34816
	ds_read_b128 v[156:159], v187 offset:35840
	ds_read_b128 v[170:173], v187 offset:36864
	ds_read_b128 v[174:177], v187 offset:37888
	ds_read_b128 v[178:181], v187 offset:38912
	ds_read_b128 v[192:195], v187 offset:39936
	global_load_lds_dwordx4 v[196:197], off
	v_lshl_add_u64 v[196:197], s[30:31], 0, v[162:163]
	s_mov_b32 m0, s50
	s_nop 0
	global_load_lds_dwordx4 v[196:197], off
	ds_read_b128 v[196:199], v190
	ds_read_b128 v[204:207], v190 offset:1024
	ds_read_b128 v[208:211], v190 offset:2048
	ds_read_b128 v[212:215], v190 offset:3072
	s_waitcnt lgkmcnt(0)
	s_waitcnt vmcnt(8)
	s_barrier
	s_setprio 1
	v_mfma_f32_16x16x32_bf16 v[124:127], v[128:131], v[144:147], v[124:127]
	v_mfma_f32_16x16x32_bf16 v[120:123], v[136:139], v[144:147], v[120:123]
	v_mfma_f32_16x16x32_bf16 v[108:111], v[128:131], v[152:155], v[108:111]
	v_mfma_f32_16x16x32_bf16 v[104:107], v[136:139], v[152:155], v[104:107]
	v_mfma_f32_16x16x32_bf16 v[92:95], v[128:131], v[170:173], v[92:95]
	v_mfma_f32_16x16x32_bf16 v[88:91], v[136:139], v[170:173], v[88:91]
	v_mfma_f32_16x16x32_bf16 v[76:79], v[128:131], v[178:181], v[76:79]
	v_mfma_f32_16x16x32_bf16 v[72:75], v[136:139], v[178:181], v[72:75]
	v_mfma_f32_16x16x32_bf16 v[124:127], v[132:135], v[148:151], v[124:127]
	v_mfma_f32_16x16x32_bf16 v[120:123], v[140:143], v[148:151], v[120:123]
	v_mfma_f32_16x16x32_bf16 v[108:111], v[132:135], v[156:159], v[108:111]
	v_mfma_f32_16x16x32_bf16 v[104:107], v[140:143], v[156:159], v[104:107]
	v_mfma_f32_16x16x32_bf16 v[92:95], v[132:135], v[174:177], v[92:95]
	v_mfma_f32_16x16x32_bf16 v[88:91], v[140:143], v[174:177], v[88:91]
	v_mfma_f32_16x16x32_bf16 v[76:79], v[132:135], v[192:195], v[76:79]
	v_mfma_f32_16x16x32_bf16 v[72:75], v[140:143], v[192:195], v[72:75]
	v_mfma_f32_16x16x32_bf16 v[116:119], v[196:199], v[144:147], v[116:119]
	v_mfma_f32_16x16x32_bf16 v[112:115], v[208:211], v[144:147], v[112:115]
	v_mfma_f32_16x16x32_bf16 v[100:103], v[196:199], v[152:155], v[100:103]
	v_mfma_f32_16x16x32_bf16 v[96:99], v[208:211], v[152:155], v[96:99]
	v_mfma_f32_16x16x32_bf16 v[84:87], v[196:199], v[170:173], v[84:87]
	v_mfma_f32_16x16x32_bf16 v[80:83], v[208:211], v[170:173], v[80:83]
	v_mfma_f32_16x16x32_bf16 v[68:71], v[196:199], v[178:181], v[68:71]
	v_mfma_f32_16x16x32_bf16 v[64:67], v[208:211], v[178:181], v[64:67]
	v_mfma_f32_16x16x32_bf16 v[116:119], v[204:207], v[148:151], v[116:119]
	v_mfma_f32_16x16x32_bf16 v[112:115], v[212:215], v[148:151], v[112:115]
	v_mfma_f32_16x16x32_bf16 v[100:103], v[204:207], v[156:159], v[100:103]
	v_mfma_f32_16x16x32_bf16 v[96:99], v[212:215], v[156:159], v[96:99]
	v_mfma_f32_16x16x32_bf16 v[84:87], v[204:207], v[174:177], v[84:87]
	v_mfma_f32_16x16x32_bf16 v[80:83], v[212:215], v[174:177], v[80:83]
	v_mfma_f32_16x16x32_bf16 v[68:71], v[204:207], v[192:195], v[68:71]
	v_mfma_f32_16x16x32_bf16 v[64:67], v[212:215], v[192:195], v[64:67]
	s_setprio 0
	s_barrier
	ds_read_b128 v[144:147], v187 offset:49152
	ds_read_b128 v[148:151], v187 offset:50176
	ds_read_b128 v[152:155], v187 offset:51200
	ds_read_b128 v[156:159], v187 offset:52224
	ds_read_b128 v[170:173], v187 offset:53248
	ds_read_b128 v[174:177], v187 offset:54272
	ds_read_b128 v[178:181], v187 offset:55296
	ds_read_b128 v[192:195], v187 offset:56320
	s_mov_b32 m0, s54
	v_lshl_add_u64 v[182:183], v[182:183], 0, s[12:13]
	global_load_lds_dwordx4 v[182:183], off
	v_lshl_add_u64 v[182:183], v[200:201], 0, s[12:13]
	s_mov_b32 m0, s55
	s_nop 0
	global_load_lds_dwordx4 v[182:183], off
	s_mov_b32 m0, s56
	v_lshl_add_u64 v[182:183], v[216:217], 0, s[12:13]
	global_load_lds_dwordx4 v[182:183], off
	v_lshl_add_u64 v[182:183], v[218:219], 0, s[12:13]
	s_mov_b32 m0, s57
	s_nop 0
	global_load_lds_dwordx4 v[182:183], off
	s_add_u32 s28, s28, 0x40080
	s_addc_u32 s29, s29, 0
	s_mov_b32 m0, s58
	v_lshl_add_u64 v[248:249], s[28:29], 0, v[160:161]
	global_load_lds_dwordx4 v[248:249], off
	v_lshl_add_u64 v[248:249], s[28:29], 0, v[162:163]
	s_mov_b32 m0, s59
	s_nop 0
	global_load_lds_dwordx4 v[248:249], off
	s_waitcnt lgkmcnt(0)
	s_waitcnt vmcnt(8)
	s_barrier
	s_setprio 1
	v_mfma_f32_16x16x32_bf16 v[60:63], v[128:131], v[144:147], v[60:63]
	v_mfma_f32_16x16x32_bf16 v[56:59], v[136:139], v[144:147], v[56:59]
	v_mfma_f32_16x16x32_bf16 v[44:47], v[128:131], v[152:155], v[44:47]
	v_mfma_f32_16x16x32_bf16 v[40:43], v[136:139], v[152:155], v[40:43]
	v_mfma_f32_16x16x32_bf16 v[28:31], v[128:131], v[170:173], v[28:31]
	v_mfma_f32_16x16x32_bf16 v[24:27], v[136:139], v[170:173], v[24:27]
	v_mfma_f32_16x16x32_bf16 v[12:15], v[128:131], v[178:181], v[12:15]
	v_mfma_f32_16x16x32_bf16 v[8:11], v[136:139], v[178:181], v[8:11]
	v_mfma_f32_16x16x32_bf16 v[60:63], v[132:135], v[148:151], v[60:63]
	v_mfma_f32_16x16x32_bf16 v[56:59], v[140:143], v[148:151], v[56:59]
	v_mfma_f32_16x16x32_bf16 v[44:47], v[132:135], v[156:159], v[44:47]
	v_mfma_f32_16x16x32_bf16 v[40:43], v[140:143], v[156:159], v[40:43]
	v_mfma_f32_16x16x32_bf16 v[28:31], v[132:135], v[174:177], v[28:31]
	v_mfma_f32_16x16x32_bf16 v[24:27], v[140:143], v[174:177], v[24:27]
	v_mfma_f32_16x16x32_bf16 v[12:15], v[132:135], v[192:195], v[12:15]
	v_mfma_f32_16x16x32_bf16 v[8:11], v[140:143], v[192:195], v[8:11]
	v_mfma_f32_16x16x32_bf16 v[52:55], v[196:199], v[144:147], v[52:55]
	v_mfma_f32_16x16x32_bf16 v[48:51], v[208:211], v[144:147], v[48:51]
	v_mfma_f32_16x16x32_bf16 v[36:39], v[196:199], v[152:155], v[36:39]
	v_mfma_f32_16x16x32_bf16 v[32:35], v[208:211], v[152:155], v[32:35]
	v_mfma_f32_16x16x32_bf16 v[20:23], v[196:199], v[170:173], v[20:23]
	v_mfma_f32_16x16x32_bf16 v[16:19], v[208:211], v[170:173], v[16:19]
	v_mfma_f32_16x16x32_bf16 v[4:7], v[196:199], v[178:181], v[4:7]
	v_mfma_f32_16x16x32_bf16 v[0:3], v[208:211], v[178:181], v[0:3]
	v_mfma_f32_16x16x32_bf16 v[52:55], v[204:207], v[148:151], v[52:55]
	v_mfma_f32_16x16x32_bf16 v[48:51], v[212:215], v[148:151], v[48:51]
	v_mfma_f32_16x16x32_bf16 v[36:39], v[204:207], v[156:159], v[36:39]
	v_mfma_f32_16x16x32_bf16 v[32:35], v[212:215], v[156:159], v[32:35]
	v_mfma_f32_16x16x32_bf16 v[20:23], v[204:207], v[174:177], v[20:23]
	v_mfma_f32_16x16x32_bf16 v[16:19], v[212:215], v[174:177], v[16:19]
	v_mfma_f32_16x16x32_bf16 v[4:7], v[204:207], v[192:195], v[4:7]
	v_mfma_f32_16x16x32_bf16 v[0:3], v[212:215], v[192:195], v[0:3]
	s_setprio 0
	s_add_i32 s40, s40, 2
	s_add_u32 s26, s26, 0x100
	s_addc_u32 s27, s27, 0
	s_add_u32 s38, s38, 0x100
	s_addc_u32 s39, s39, 0
	s_cmp_gt_u32 s40, 13
	s_barrier
	s_cbranch_scc0 .LBB0_883
	s_and_b64 vcc, exec, s[18:19]
	s_cbranch_vccnz .Lp5_noA
	s_add_u32 s80, s14, 0x40080
	s_addc_u32 s81, s15, 0
	v_lshl_add_u64 v[182:183], s[80:81], 0, v[164:165]
	s_add_i32 m0, s45, 0xc000
	s_nop 0
	global_load_lds_dwordx4 v[182:183], off
	v_lshl_add_u64 v[182:183], s[80:81], 0, v[166:167]
	s_add_i32 m0, s45, 0xe000
	s_nop 0
	global_load_lds_dwordx4 v[182:183], off
.Lp5_noA:
	v_lshl_or_b32 v128, s65, 8, v185
	v_lshl_add_u32 v170, s24, 8, v184
	v_ashrrev_i32_e32 v129, 31, v128
	v_lshlrev_b64 v[174:175], 1, v[128:129]
	v_ashrrev_i32_e32 v171, 31, v170
	v_lshl_add_u64 v[128:129], s[10:11], 0, v[174:175]
	v_lshlrev_b64 v[204:205], 11, v[170:171]
	v_lshl_add_u64 v[130:131], v[128:129], 0, v[204:205]
	v_mov_b32_e32 v194, v220
	v_mov_b32_e32 v195, v221
	v_mov_b32_e32 v196, v222
	v_mov_b32_e32 v197, v223
	v_mov_b32_e32 v198, v224
	v_mov_b32_e32 v199, v225
	v_mov_b32_e32 v200, v226
	v_mov_b32_e32 v201, v227
	v_or_b32_e32 v130, 16, v170
	v_or_b32_e32 v132, 32, v170
	v_or_b32_e32 v134, 48, v170
	v_ashrrev_i32_e32 v131, 31, v130
	v_ashrrev_i32_e32 v133, 31, v132
	v_ashrrev_i32_e32 v135, 31, v134
	v_lshlrev_b64 v[182:183], 11, v[130:131]
	v_add_u32_e32 v178, 0x80, v170
	v_lshlrev_b64 v[180:181], 11, v[132:133]
	v_lshlrev_b64 v[176:177], 11, v[134:135]
	v_lshl_add_u64 v[132:133], v[128:129], 0, v[182:183]
	v_ashrrev_i32_e32 v179, 31, v178
	v_lshl_add_u64 v[134:135], v[128:129], 0, v[180:181]
	v_lshl_add_u64 v[128:129], v[128:129], 0, v[176:177]
	v_mov_b32_e32 v156, v228
	v_mov_b32_e32 v157, v229
	v_mov_b32_e32 v158, v230
	v_mov_b32_e32 v159, v231
	v_mov_b32_e32 v152, v232
	v_mov_b32_e32 v153, v233
	v_mov_b32_e32 v154, v234
	v_mov_b32_e32 v155, v235
	v_mov_b32_e32 v148, v236
	v_mov_b32_e32 v149, v237
	v_mov_b32_e32 v150, v238
	v_mov_b32_e32 v151, v239
	v_mov_b32_e32 v144, v240
	v_mov_b32_e32 v145, v241
	v_mov_b32_e32 v146, v242
	v_mov_b32_e32 v147, v243
	v_mov_b32_e32 v140, v252
	v_mov_b32_e32 v141, v253
	v_mov_b32_e32 v142, v254
	v_mov_b32_e32 v143, v255
	global_load_dwordx4 v[136:139], v[128:129], off offset:64
	v_lshlrev_b64 v[130:131], 11, v[178:179]
	v_lshl_add_u64 v[130:131], s[10:11], 0, v[130:131]
	v_lshl_add_u64 v[172:173], v[130:131], 0, v[174:175]
	global_load_dwordx4 v[132:135], v[172:173], off
	global_load_dwordx4 v[128:131], v[172:173], off offset:64
	v_and_b32_e32 v192, 64, v191
	v_xor_b32_e32 v179, 16, v191
	v_add_u32_e32 v192, 64, v192
	v_xor_b32_e32 v193, 32, v191
	v_cmp_lt_i32_e32 vcc, v179, v192
	v_lshl_add_u64 v[204:205], s[10:11], 0, v[204:205]
	v_lshl_add_u64 v[204:205], v[204:205], 0, v[174:175]
	v_cndmask_b32_e32 v179, v191, v179, vcc
	v_cmp_lt_i32_e32 vcc, v193, v192
	v_lshlrev_b32_e32 v192, 2, v179
	s_lshl_b32 s24, s65, 2
	v_cndmask_b32_e32 v193, v191, v193, vcc
	v_lshlrev_b32_e32 v179, 2, v193
	s_or_b32 s27, s24, s53
	s_mul_hi_i32 s26, s27, 0x21000
	s_mul_i32 s27, s27, 0x21000
	v_lshlrev_b32_e32 v206, 16, v194
	v_and_b32_e32 v207, 0xffff0000, v194
	v_lshlrev_b32_e32 v194, 16, v195
	v_and_b32_e32 v195, 0xffff0000, v195
	v_lshlrev_b32_e32 v208, 16, v196
	v_and_b32_e32 v209, 0xffff0000, v196
	v_lshlrev_b32_e32 v196, 16, v197
	v_and_b32_e32 v197, 0xffff0000, v197
	v_lshlrev_b32_e32 v212, 16, v200
	v_and_b32_e32 v213, 0xffff0000, v200
	v_lshlrev_b32_e32 v200, 16, v201
	v_and_b32_e32 v201, 0xffff0000, v201
	v_pk_add_f32 v[126:127], v[126:127], v[194:195]
	v_pk_add_f32 v[124:125], v[124:125], v[206:207]
	v_pk_add_f32 v[122:123], v[122:123], v[196:197]
	v_pk_add_f32 v[120:121], v[120:121], v[208:209]
	v_lshlrev_b32_e32 v210, 16, v198
	v_and_b32_e32 v211, 0xffff0000, v198
	v_lshlrev_b32_e32 v198, 16, v199
	v_and_b32_e32 v199, 0xffff0000, v199
	v_pk_add_f32 v[194:195], v[114:115], v[200:201]
	v_pk_add_f32 v[196:197], v[112:113], v[212:213]
	v_cvt_pk_bf16_f32 v112, v124, v125
	v_cvt_pk_bf16_f32 v113, v126, v127
	v_mul_f32_e32 v114, v125, v125
	v_mul_f32_e32 v115, v127, v127
	v_mul_f32_e32 v125, v121, v121
	v_mul_f32_e32 v127, v123, v123
	v_pk_add_f32 v[118:119], v[118:119], v[198:199]
	v_pk_add_f32 v[116:117], v[116:117], v[210:211]
	v_fmac_f32_e32 v114, v124, v124
	v_fmac_f32_e32 v115, v126, v126
	v_fmac_f32_e32 v125, v120, v120
	v_fmac_f32_e32 v127, v122, v122
	v_mul_f32_e32 v193, v117, v117
	v_mul_f32_e32 v198, v119, v119
	v_add_f32_e32 v114, v114, v115
	v_add_f32_e32 v115, v125, v127
	v_mul_f32_e32 v124, v197, v197
	v_mul_f32_e32 v125, v195, v195
	v_fmac_f32_e32 v193, v116, v116
	v_fmac_f32_e32 v198, v118, v118
	v_fmac_f32_e32 v124, v196, v196
	v_fmac_f32_e32 v125, v194, v194
	v_add_f32_e32 v114, v114, v115
	v_add_f32_e32 v115, v193, v198
	v_add_f32_e32 v124, v124, v125
	v_add_f32_e32 v115, v115, v124
	v_add_f32_e32 v124, v114, v115
	ds_bpermute_b32 v125, v192, v124
	v_cvt_pk_bf16_f32 v114, v120, v121
	v_cvt_pk_bf16_f32 v115, v122, v123
	global_store_dwordx4 v[204:205], v[112:115], off
	s_waitcnt lgkmcnt(0)
	s_nop 0
	v_add_f32_e32 v112, v124, v125
	ds_bpermute_b32 v113, v179, v112
	v_cvt_pk_bf16_f32 v114, v116, v117
	v_cvt_pk_bf16_f32 v115, v118, v119
	v_cvt_pk_bf16_f32 v116, v196, v197
	v_cvt_pk_bf16_f32 v117, v194, v195
	global_store_dwordx4 v[204:205], v[114:117], off offset:64
	s_and_saveexec_b64 s[24:25], s[4:5]
	s_cbranch_execz .LBB0_886
	s_add_u32 s28, s51, s27
	s_addc_u32 s29, s52, s26
	s_waitcnt lgkmcnt(0)
	v_add_f32_e32 v114, v112, v113
	v_lshl_add_u64 v[112:113], v[170:171], 2, s[28:29]
	global_store_dword v[112:113], v114, off

.LBB0_1121:
	s_add_u32 s8, s22, 0x1c00000
	s_addc_u32 s9, s23, 0
	s_add_u32 s48, s22, 0x18db4000
	v_readlane_b32 s29, v246, 0
	s_addc_u32 s49, s23, 0
	s_add_i32 s19, s29, 0x18000
	s_and_b32 s50, s10, 3
	s_add_i32 s51, s19, s5
	s_mov_b64 s[10:11], 0x80
	s_lshl_b32 s16, s4, 13
	s_lshl_b32 s17, s50, 12
	v_lshl_add_u64 v[6:7], v[6:7], 0, s[10:11]
	s_mov_b32 m0, s51
	s_add_i32 s52, s51, 0x2000
	s_add_i32 s53, s42, 0x8000
	s_add_i32 s54, s42, 0xa000
	global_load_lds_dwordx4 v[6:7], off
	v_lshl_add_u64 v[4:5], v[4:5], 0, s[10:11]
	s_mov_b32 m0, s52
	s_add_u32 s14, s26, 0x20080
	global_load_lds_dwordx4 v[4:5], off
	v_lshl_add_u64 v[2:3], v[2:3], 0, s[10:11]
	s_mov_b32 m0, s53
	s_addc_u32 s15, s27, 0
	s_add_i32 s28, s29, 0x1c000
	global_load_lds_dwordx4 v[2:3], off
	v_lshl_add_u64 v[0:1], v[0:1], 0, s[10:11]
	s_mov_b32 m0, s54
	s_add_i32 s55, s28, s5
	global_load_lds_dwordx4 v[0:1], off
	v_lshl_add_u64 v[0:1], s[14:15], 0, v[160:161]
	s_mov_b32 m0, s55
	s_add_i32 s56, s55, 0x2000
	global_load_lds_dwordx4 v[0:1], off
	v_lshl_add_u64 v[0:1], s[14:15], 0, v[162:163]
	s_mov_b32 m0, s56
	v_lshlrev_b32_e32 v5, 6, v202
	global_load_lds_dwordx4 v[0:1], off
	s_waitcnt vmcnt(8)
	s_barrier
	v_bfe_u32 v0, v202, 4, 2
	v_and_b32_e32 v1, 15, v202
	s_waitcnt vmcnt(0)
	v_lshl_or_b32 v184, s4, 6, v1
	v_lshlrev_b32_e32 v3, 4, v0
	s_movk_i32 s4, 0x3c0
	v_lshlrev_b32_e32 v2, 3, v0
	v_lshl_or_b32 v1, v1, 6, v3
	v_and_or_b32 v3, v5, s4, v3
	v_cmp_eq_u32_e64 s[4:5], 0, v0
	v_lshlrev_b32_e32 v0, 7, v202
	v_lshl_or_b32 v185, s50, 6, v2
	v_and_b32_e32 v0, 0xffffc000, v0
	v_lshlrev_b32_e32 v2, 10, v10
	v_or3_b32 v0, v8, v0, v2
	v_add_u32_e32 v164, v0, v9
	v_lshlrev_b32_e32 v0, 3, v11
	v_lshlrev_b32_e32 v4, 2, v202
	v_and_b32_e32 v0, 0xffffc000, v0
	v_and_b32_e32 v4, 32, v4
	s_waitcnt vmcnt(6)
	v_or3_b32 v0, v8, v0, v2
	v_bitop3_b32 v1, v1, s16, v4 bitop3:0xde
	v_bitop3_b32 v3, s17, v3, v4 bitop3:0xf6
	v_readlane_b32 s14, v246, 1
	v_add_u32_e32 v166, v0, v9
	v_mbcnt_lo_u32_b32 v0, -1, 0
	s_mov_b32 s57, 0
	v_readlane_b32 s15, v246, 2
	s_ashr_i32 s58, s14, 31
	s_mov_b32 s59, s14
	s_ashr_i32 s60, s30, 31
	v_mov_b32_e32 v165, v161
	v_mov_b32_e32 v167, v161
	v_mov_b64_e32 v[168:169], 0x20f
	s_movk_i32 s61, 0x43
	v_add_u32_e32 v186, s12, v3
	v_add_u32_e32 v187, s29, v1
	v_add_u32_e32 v188, s13, v3
	v_add_u32_e32 v189, s19, v3
	v_add_u32_e32 v190, s28, v3
	v_mbcnt_hi_u32_b32 v191, -1, v0
	s_barrier
	s_add_u32 s80, s24, 0x20080
	s_addc_u32 s81, s25, 0
	v_lshl_add_u64 v[182:183], s[80:81], 0, v[164:165]
	s_add_i32 m0, s42, 0xc000
	s_nop 0
	global_load_lds_dwordx4 v[182:183], off
	v_lshl_add_u64 v[182:183], s[80:81], 0, v[166:167]
	s_add_i32 m0, s42, 0xe000
	s_nop 0
	global_load_lds_dwordx4 v[182:183], off
	s_waitcnt vmcnt(0)
	s_branch .LBB0_1123

.LBB0_1127:
	s_xor_b64 s[16:17], s[34:35], -1
	s_and_b64 s[28:29], s[34:35], exec
	s_cselect_b32 s19, s13, s25
	s_cselect_b32 s30, s12, s24
	s_cselect_b32 s34, s15, s27
	s_cselect_b32 s35, s14, s26
	s_add_u32 s24, s24, 0x20080
	s_addc_u32 s25, s25, 0
	s_add_u32 s36, s26, 0x100
	s_addc_u32 s37, s27, 0
	s_mov_b32 s38, -2
	s_waitcnt lgkmcnt(0)
	ds_read_b128 v[128:131], v186
	ds_read_b128 v[132:135], v186 offset:1024
	ds_read_b128 v[136:139], v186 offset:2048
	ds_read_b128 v[140:143], v186 offset:3072
	s_add_u32 s26, s24, 0xfffe0080
	s_addc_u32 s27, s25, -1
	s_cmp_eq_u32 s38, 4
	s_cselect_b32 s29, s19, s27
	s_cselect_b32 s28, s30, s26
	s_cselect_b32 s27, s34, s37
	s_cselect_b32 s26, s35, s36
	ds_read_b128 v[144:147], v187
	ds_read_b128 v[148:151], v187 offset:1024
	ds_read_b128 v[152:155], v187 offset:2048
	ds_read_b128 v[156:159], v187 offset:3072
	ds_read_b128 v[170:173], v187 offset:4096
	ds_read_b128 v[174:177], v187 offset:5120
	ds_read_b128 v[178:181], v187 offset:6144
	ds_read_b128 v[192:195], v187 offset:7168
	ds_read_b128 v[196:199], v188
	ds_read_b128 v[204:207], v188 offset:1024
	ds_read_b128 v[208:211], v188 offset:2048
	ds_read_b128 v[212:215], v188 offset:3072
	s_waitcnt lgkmcnt(0)
	s_nop 0
	s_barrier
	s_setprio 1
	v_mfma_f32_16x16x32_bf16 v[124:127], v[128:131], v[144:147], 0
	v_mfma_f32_16x16x32_bf16 v[120:123], v[136:139], v[144:147], 0
	v_mfma_f32_16x16x32_bf16 v[108:111], v[128:131], v[152:155], 0
	v_mfma_f32_16x16x32_bf16 v[104:107], v[136:139], v[152:155], 0
	v_mfma_f32_16x16x32_bf16 v[92:95], v[128:131], v[170:173], 0
	v_mfma_f32_16x16x32_bf16 v[88:91], v[136:139], v[170:173], 0
	v_mfma_f32_16x16x32_bf16 v[76:79], v[128:131], v[178:181], 0
	v_mfma_f32_16x16x32_bf16 v[72:75], v[136:139], v[178:181], 0
	v_mfma_f32_16x16x32_bf16 v[124:127], v[132:135], v[148:151], v[124:127]
	v_mfma_f32_16x16x32_bf16 v[120:123], v[140:143], v[148:151], v[120:123]
	v_mfma_f32_16x16x32_bf16 v[108:111], v[132:135], v[156:159], v[108:111]
	v_mfma_f32_16x16x32_bf16 v[104:107], v[140:143], v[156:159], v[104:107]
	v_mfma_f32_16x16x32_bf16 v[92:95], v[132:135], v[174:177], v[92:95]
	v_mfma_f32_16x16x32_bf16 v[88:91], v[140:143], v[174:177], v[88:91]
	v_mfma_f32_16x16x32_bf16 v[76:79], v[132:135], v[192:195], v[76:79]
	v_mfma_f32_16x16x32_bf16 v[72:75], v[140:143], v[192:195], v[72:75]
	v_mfma_f32_16x16x32_bf16 v[116:119], v[196:199], v[144:147], 0
	v_mfma_f32_16x16x32_bf16 v[112:115], v[208:211], v[144:147], 0
	v_mfma_f32_16x16x32_bf16 v[100:103], v[196:199], v[152:155], 0
	v_mfma_f32_16x16x32_bf16 v[96:99], v[208:211], v[152:155], 0
	v_mfma_f32_16x16x32_bf16 v[84:87], v[196:199], v[170:173], 0
	v_mfma_f32_16x16x32_bf16 v[80:83], v[208:211], v[170:173], 0
	v_mfma_f32_16x16x32_bf16 v[68:71], v[196:199], v[178:181], 0
	v_mfma_f32_16x16x32_bf16 v[64:67], v[208:211], v[178:181], 0
	v_mfma_f32_16x16x32_bf16 v[116:119], v[204:207], v[148:151], v[116:119]
	v_mfma_f32_16x16x32_bf16 v[112:115], v[212:215], v[148:151], v[112:115]
	v_mfma_f32_16x16x32_bf16 v[100:103], v[204:207], v[156:159], v[100:103]
	v_mfma_f32_16x16x32_bf16 v[96:99], v[212:215], v[156:159], v[96:99]
	v_mfma_f32_16x16x32_bf16 v[84:87], v[204:207], v[174:177], v[84:87]
	v_mfma_f32_16x16x32_bf16 v[80:83], v[212:215], v[174:177], v[80:83]
	v_mfma_f32_16x16x32_bf16 v[68:71], v[204:207], v[192:195], v[68:71]
	v_mfma_f32_16x16x32_bf16 v[64:67], v[212:215], v[192:195], v[64:67]
	s_setprio 0
	s_barrier
	v_lshl_or_b32 v203, s63, 8, v185
	v_lshlrev_b32_e32 v203, 1, v203
	v_lshl_add_u32 v247, s18, 8, v184
	v_lshl_add_u32 v203, v247, 11, v203
	s_add_u32 s74, s8, 0x8000
	s_addc_u32 s75, s9, 0
	s_add_u32 s76, s8, 0x10000
	s_addc_u32 s77, s9, 0
	s_add_u32 s78, s8, 0x18000
	s_addc_u32 s79, s9, 0
	global_load_dwordx4 v[220:223], v203, s[8:9]
	global_load_dwordx4 v[224:227], v203, s[8:9] offset:64
	global_load_dwordx4 v[228:231], v203, s[74:75]
	global_load_dwordx4 v[232:235], v203, s[74:75] offset:64
	global_load_dwordx4 v[236:239], v203, s[76:77]
	global_load_dwordx4 v[240:243], v203, s[76:77] offset:64
	global_load_dwordx4 v[252:255], v203, s[78:79]
	ds_read_b128 v[144:147], v187 offset:16384
	ds_read_b128 v[148:151], v187 offset:17408
	ds_read_b128 v[152:155], v187 offset:18432
	ds_read_b128 v[156:159], v187 offset:19456
	ds_read_b128 v[170:173], v187 offset:20480
	ds_read_b128 v[174:177], v187 offset:21504
	ds_read_b128 v[178:181], v187 offset:22528
	ds_read_b128 v[192:195], v187 offset:23552
	s_mov_b32 m0, s40
	v_lshl_add_u64 v[182:183], s[26:27], 0, v[160:161]
	global_load_lds_dwordx4 v[182:183], off
	v_lshl_add_u64 v[200:201], s[26:27], 0, v[162:163]
	s_mov_b32 m0, s41
	s_nop 0
	global_load_lds_dwordx4 v[200:201], off
	s_mov_b32 m0, s42
	v_lshl_add_u64 v[216:217], s[28:29], 0, v[160:161]
	global_load_lds_dwordx4 v[216:217], off
	v_lshl_add_u64 v[218:219], s[28:29], 0, v[162:163]
	s_mov_b32 m0, s43
	s_nop 0
	global_load_lds_dwordx4 v[218:219], off
	s_add_u32 s64, s26, 0x20000
	s_addc_u32 s65, s27, 0
	s_mov_b32 m0, s44
	v_lshl_add_u64 v[248:249], s[64:65], 0, v[160:161]
	global_load_lds_dwordx4 v[248:249], off
	v_lshl_add_u64 v[248:249], s[64:65], 0, v[162:163]
	s_mov_b32 m0, s45
	s_nop 0
	global_load_lds_dwordx4 v[248:249], off
	s_waitcnt lgkmcnt(0)
	s_nop 0
	s_barrier
	s_setprio 1
	v_mfma_f32_16x16x32_bf16 v[60:63], v[128:131], v[144:147], 0
	v_mfma_f32_16x16x32_bf16 v[56:59], v[136:139], v[144:147], 0
	v_mfma_f32_16x16x32_bf16 v[44:47], v[128:131], v[152:155], 0
	v_mfma_f32_16x16x32_bf16 v[40:43], v[136:139], v[152:155], 0
	v_mfma_f32_16x16x32_bf16 v[28:31], v[128:131], v[170:173], 0
	v_mfma_f32_16x16x32_bf16 v[24:27], v[136:139], v[170:173], 0
	v_mfma_f32_16x16x32_bf16 v[12:15], v[128:131], v[178:181], 0
	v_mfma_f32_16x16x32_bf16 v[8:11], v[136:139], v[178:181], 0
	v_mfma_f32_16x16x32_bf16 v[60:63], v[132:135], v[148:151], v[60:63]
	v_mfma_f32_16x16x32_bf16 v[56:59], v[140:143], v[148:151], v[56:59]
	v_mfma_f32_16x16x32_bf16 v[44:47], v[132:135], v[156:159], v[44:47]
	v_mfma_f32_16x16x32_bf16 v[40:43], v[140:143], v[156:159], v[40:43]
	v_mfma_f32_16x16x32_bf16 v[28:31], v[132:135], v[174:177], v[28:31]
	v_mfma_f32_16x16x32_bf16 v[24:27], v[140:143], v[174:177], v[24:27]
	v_mfma_f32_16x16x32_bf16 v[12:15], v[132:135], v[192:195], v[12:15]
	v_mfma_f32_16x16x32_bf16 v[8:11], v[140:143], v[192:195], v[8:11]
	v_mfma_f32_16x16x32_bf16 v[52:55], v[196:199], v[144:147], 0
	v_mfma_f32_16x16x32_bf16 v[48:51], v[208:211], v[144:147], 0
	v_mfma_f32_16x16x32_bf16 v[36:39], v[196:199], v[152:155], 0
	v_mfma_f32_16x16x32_bf16 v[32:35], v[208:211], v[152:155], 0
	v_mfma_f32_16x16x32_bf16 v[20:23], v[196:199], v[170:173], 0
	v_mfma_f32_16x16x32_bf16 v[16:19], v[208:211], v[170:173], 0
	v_mfma_f32_16x16x32_bf16 v[4:7], v[196:199], v[178:181], 0
	v_mfma_f32_16x16x32_bf16 v[0:3], v[208:211], v[178:181], 0
	v_mfma_f32_16x16x32_bf16 v[52:55], v[204:207], v[148:151], v[52:55]
	v_mfma_f32_16x16x32_bf16 v[48:51], v[212:215], v[148:151], v[48:51]
	v_mfma_f32_16x16x32_bf16 v[36:39], v[204:207], v[156:159], v[36:39]
	v_mfma_f32_16x16x32_bf16 v[32:35], v[212:215], v[156:159], v[32:35]
	v_mfma_f32_16x16x32_bf16 v[20:23], v[204:207], v[174:177], v[20:23]
	v_mfma_f32_16x16x32_bf16 v[16:19], v[212:215], v[174:177], v[16:19]
	v_mfma_f32_16x16x32_bf16 v[4:7], v[204:207], v[192:195], v[4:7]
	v_mfma_f32_16x16x32_bf16 v[0:3], v[212:215], v[192:195], v[0:3]
	s_setprio 0
	s_barrier
	ds_read_b128 v[128:131], v189
	ds_read_b128 v[132:135], v189 offset:1024
	ds_read_b128 v[136:139], v189 offset:2048
	ds_read_b128 v[140:143], v189 offset:3072
	s_add_u32 s28, s28, 0x20000
	s_addc_u32 s29, s29, 0
	s_mov_b32 m0, s46
	v_lshl_add_u64 v[196:197], s[28:29], 0, v[160:161]
	ds_read_b128 v[144:147], v187 offset:32768
	ds_read_b128 v[148:151], v187 offset:33792
	ds_read_b128 v[152:155], v187 offset:34816
	ds_read_b128 v[156:159], v187 offset:35840
	ds_read_b128 v[170:173], v187 offset:36864
	ds_read_b128 v[174:177], v187 offset:37888
	ds_read_b128 v[178:181], v187 offset:38912
	ds_read_b128 v[192:195], v187 offset:39936
	global_load_lds_dwordx4 v[196:197], off
	v_lshl_add_u64 v[196:197], s[28:29], 0, v[162:163]
	s_mov_b32 m0, s47
	s_nop 0
	global_load_lds_dwordx4 v[196:197], off
	ds_read_b128 v[196:199], v190
	ds_read_b128 v[204:207], v190 offset:1024
	ds_read_b128 v[208:211], v190 offset:2048
	ds_read_b128 v[212:215], v190 offset:3072
	s_waitcnt lgkmcnt(0)
	s_nop 0
	s_barrier
	s_setprio 1
	v_mfma_f32_16x16x32_bf16 v[124:127], v[128:131], v[144:147], v[124:127]
	v_mfma_f32_16x16x32_bf16 v[120:123], v[136:139], v[144:147], v[120:123]
	v_mfma_f32_16x16x32_bf16 v[108:111], v[128:131], v[152:155], v[108:111]
	v_mfma_f32_16x16x32_bf16 v[104:107], v[136:139], v[152:155], v[104:107]
	v_mfma_f32_16x16x32_bf16 v[92:95], v[128:131], v[170:173], v[92:95]
	v_mfma_f32_16x16x32_bf16 v[88:91], v[136:139], v[170:173], v[88:91]
	v_mfma_f32_16x16x32_bf16 v[76:79], v[128:131], v[178:181], v[76:79]
	v_mfma_f32_16x16x32_bf16 v[72:75], v[136:139], v[178:181], v[72:75]
	v_mfma_f32_16x16x32_bf16 v[124:127], v[132:135], v[148:151], v[124:127]
	v_mfma_f32_16x16x32_bf16 v[120:123], v[140:143], v[148:151], v[120:123]
	v_mfma_f32_16x16x32_bf16 v[108:111], v[132:135], v[156:159], v[108:111]
	v_mfma_f32_16x16x32_bf16 v[104:107], v[140:143], v[156:159], v[104:107]
	v_mfma_f32_16x16x32_bf16 v[92:95], v[132:135], v[174:177], v[92:95]
	v_mfma_f32_16x16x32_bf16 v[88:91], v[140:143], v[174:177], v[88:91]
	v_mfma_f32_16x16x32_bf16 v[76:79], v[132:135], v[192:195], v[76:79]
	v_mfma_f32_16x16x32_bf16 v[72:75], v[140:143], v[192:195], v[72:75]
	v_mfma_f32_16x16x32_bf16 v[116:119], v[196:199], v[144:147], v[116:119]
	v_mfma_f32_16x16x32_bf16 v[112:115], v[208:211], v[144:147], v[112:115]
	v_mfma_f32_16x16x32_bf16 v[100:103], v[196:199], v[152:155], v[100:103]
	v_mfma_f32_16x16x32_bf16 v[96:99], v[208:211], v[152:155], v[96:99]
	v_mfma_f32_16x16x32_bf16 v[84:87], v[196:199], v[170:173], v[84:87]
	v_mfma_f32_16x16x32_bf16 v[80:83], v[208:211], v[170:173], v[80:83]
	v_mfma_f32_16x16x32_bf16 v[68:71], v[196:199], v[178:181], v[68:71]
	v_mfma_f32_16x16x32_bf16 v[64:67], v[208:211], v[178:181], v[64:67]
	v_mfma_f32_16x16x32_bf16 v[116:119], v[204:207], v[148:151], v[116:119]
	v_mfma_f32_16x16x32_bf16 v[112:115], v[212:215], v[148:151], v[112:115]
	v_mfma_f32_16x16x32_bf16 v[100:103], v[204:207], v[156:159], v[100:103]
	v_mfma_f32_16x16x32_bf16 v[96:99], v[212:215], v[156:159], v[96:99]
	v_mfma_f32_16x16x32_bf16 v[84:87], v[204:207], v[174:177], v[84:87]
	v_mfma_f32_16x16x32_bf16 v[80:83], v[212:215], v[174:177], v[80:83]
	v_mfma_f32_16x16x32_bf16 v[68:71], v[204:207], v[192:195], v[68:71]
	v_mfma_f32_16x16x32_bf16 v[64:67], v[212:215], v[192:195], v[64:67]
	s_setprio 0
	s_barrier
	ds_read_b128 v[144:147], v187 offset:49152
	ds_read_b128 v[148:151], v187 offset:50176
	ds_read_b128 v[152:155], v187 offset:51200
	ds_read_b128 v[156:159], v187 offset:52224
	ds_read_b128 v[170:173], v187 offset:53248
	ds_read_b128 v[174:177], v187 offset:54272
	ds_read_b128 v[178:181], v187 offset:55296
	ds_read_b128 v[192:195], v187 offset:56320
	s_mov_b32 m0, s51
	v_lshl_add_u64 v[182:183], v[182:183], 0, s[10:11]
	global_load_lds_dwordx4 v[182:183], off
	v_lshl_add_u64 v[182:183], v[200:201], 0, s[10:11]
	s_mov_b32 m0, s52
	s_nop 0
	global_load_lds_dwordx4 v[182:183], off
	s_mov_b32 m0, s53
	v_lshl_add_u64 v[182:183], v[216:217], 0, s[10:11]
	global_load_lds_dwordx4 v[182:183], off
	v_lshl_add_u64 v[182:183], v[218:219], 0, s[10:11]
	s_mov_b32 m0, s54
	s_nop 0
	global_load_lds_dwordx4 v[182:183], off
	s_add_u32 s26, s26, 0x20080
	s_addc_u32 s27, s27, 0
	s_mov_b32 m0, s55
	v_lshl_add_u64 v[248:249], s[26:27], 0, v[160:161]
	global_load_lds_dwordx4 v[248:249], off
	v_lshl_add_u64 v[248:249], s[26:27], 0, v[162:163]
	s_mov_b32 m0, s56
	s_nop 0
	global_load_lds_dwordx4 v[248:249], off
	s_waitcnt lgkmcnt(0)
	s_waitcnt vmcnt(8)
	s_barrier
	s_setprio 1
	v_mfma_f32_16x16x32_bf16 v[60:63], v[128:131], v[144:147], v[60:63]
	v_mfma_f32_16x16x32_bf16 v[56:59], v[136:139], v[144:147], v[56:59]
	v_mfma_f32_16x16x32_bf16 v[44:47], v[128:131], v[152:155], v[44:47]
	v_mfma_f32_16x16x32_bf16 v[40:43], v[136:139], v[152:155], v[40:43]
	v_mfma_f32_16x16x32_bf16 v[28:31], v[128:131], v[170:173], v[28:31]
	v_mfma_f32_16x16x32_bf16 v[24:27], v[136:139], v[170:173], v[24:27]
	v_mfma_f32_16x16x32_bf16 v[12:15], v[128:131], v[178:181], v[12:15]
	v_mfma_f32_16x16x32_bf16 v[8:11], v[136:139], v[178:181], v[8:11]
	v_mfma_f32_16x16x32_bf16 v[60:63], v[132:135], v[148:151], v[60:63]
	v_mfma_f32_16x16x32_bf16 v[56:59], v[140:143], v[148:151], v[56:59]
	v_mfma_f32_16x16x32_bf16 v[44:47], v[132:135], v[156:159], v[44:47]
	v_mfma_f32_16x16x32_bf16 v[40:43], v[140:143], v[156:159], v[40:43]
	v_mfma_f32_16x16x32_bf16 v[28:31], v[132:135], v[174:177], v[28:31]
	v_mfma_f32_16x16x32_bf16 v[24:27], v[140:143], v[174:177], v[24:27]
	v_mfma_f32_16x16x32_bf16 v[12:15], v[132:135], v[192:195], v[12:15]
	v_mfma_f32_16x16x32_bf16 v[8:11], v[140:143], v[192:195], v[8:11]
	v_mfma_f32_16x16x32_bf16 v[52:55], v[196:199], v[144:147], v[52:55]
	v_mfma_f32_16x16x32_bf16 v[48:51], v[208:211], v[144:147], v[48:51]
	v_mfma_f32_16x16x32_bf16 v[36:39], v[196:199], v[152:155], v[36:39]
	v_mfma_f32_16x16x32_bf16 v[32:35], v[208:211], v[152:155], v[32:35]
	v_mfma_f32_16x16x32_bf16 v[20:23], v[196:199], v[170:173], v[20:23]
	v_mfma_f32_16x16x32_bf16 v[16:19], v[208:211], v[170:173], v[16:19]
	v_mfma_f32_16x16x32_bf16 v[4:7], v[196:199], v[178:181], v[4:7]
	v_mfma_f32_16x16x32_bf16 v[0:3], v[208:211], v[178:181], v[0:3]
	v_mfma_f32_16x16x32_bf16 v[52:55], v[204:207], v[148:151], v[52:55]
	v_mfma_f32_16x16x32_bf16 v[48:51], v[212:215], v[148:151], v[48:51]
	v_mfma_f32_16x16x32_bf16 v[36:39], v[204:207], v[156:159], v[36:39]
	v_mfma_f32_16x16x32_bf16 v[32:35], v[212:215], v[156:159], v[32:35]
	v_mfma_f32_16x16x32_bf16 v[20:23], v[204:207], v[174:177], v[20:23]
	v_mfma_f32_16x16x32_bf16 v[16:19], v[212:215], v[174:177], v[16:19]
	v_mfma_f32_16x16x32_bf16 v[4:7], v[204:207], v[192:195], v[4:7]
	v_mfma_f32_16x16x32_bf16 v[0:3], v[212:215], v[192:195], v[0:3]
	s_setprio 0
	s_add_i32 s38, s38, 2
	s_add_u32 s24, s24, 0x100
	s_addc_u32 s25, s25, 0
	s_add_u32 s36, s36, 0x100
	s_addc_u32 s37, s37, 0
	s_cmp_gt_u32 s38, 5
	s_barrier
.LBB0_1128:
	ds_read_b128 v[128:131], v186
	ds_read_b128 v[132:135], v186 offset:1024
	ds_read_b128 v[136:139], v186 offset:2048
	ds_read_b128 v[140:143], v186 offset:3072
	s_add_u32 s26, s24, 0xfffe0080
	s_addc_u32 s27, s25, -1
	s_cmp_eq_u32 s38, 4
	s_cselect_b32 s29, s19, s27
	s_cselect_b32 s28, s30, s26
	s_cselect_b32 s27, s34, s37
	s_cselect_b32 s26, s35, s36
	v_lshl_add_u64 v[182:183], s[24:25], 0, v[164:165]
	s_add_i32 m0, s42, 0xc000
	ds_read_b128 v[144:147], v187
	ds_read_b128 v[148:151], v187 offset:1024
	ds_read_b128 v[152:155], v187 offset:2048
	ds_read_b128 v[156:159], v187 offset:3072
	ds_read_b128 v[170:173], v187 offset:4096
	ds_read_b128 v[174:177], v187 offset:5120
	ds_read_b128 v[178:181], v187 offset:6144
	ds_read_b128 v[192:195], v187 offset:7168
	global_load_lds_dwordx4 v[182:183], off
	v_lshl_add_u64 v[182:183], s[24:25], 0, v[166:167]
	s_add_i32 m0, s42, 0xe000
	s_nop 0
	global_load_lds_dwordx4 v[182:183], off
	ds_read_b128 v[196:199], v188
	ds_read_b128 v[204:207], v188 offset:1024
	ds_read_b128 v[208:211], v188 offset:2048
	ds_read_b128 v[212:215], v188 offset:3072
	s_waitcnt lgkmcnt(0)
	s_waitcnt vmcnt(8)
	s_barrier
	s_setprio 1
	v_mfma_f32_16x16x32_bf16 v[124:127], v[128:131], v[144:147], v[124:127]
	v_mfma_f32_16x16x32_bf16 v[120:123], v[136:139], v[144:147], v[120:123]
	v_mfma_f32_16x16x32_bf16 v[108:111], v[128:131], v[152:155], v[108:111]
	v_mfma_f32_16x16x32_bf16 v[104:107], v[136:139], v[152:155], v[104:107]
	v_mfma_f32_16x16x32_bf16 v[92:95], v[128:131], v[170:173], v[92:95]
	v_mfma_f32_16x16x32_bf16 v[88:91], v[136:139], v[170:173], v[88:91]
	v_mfma_f32_16x16x32_bf16 v[76:79], v[128:131], v[178:181], v[76:79]
	v_mfma_f32_16x16x32_bf16 v[72:75], v[136:139], v[178:181], v[72:75]
	v_mfma_f32_16x16x32_bf16 v[124:127], v[132:135], v[148:151], v[124:127]
	v_mfma_f32_16x16x32_bf16 v[120:123], v[140:143], v[148:151], v[120:123]
	v_mfma_f32_16x16x32_bf16 v[108:111], v[132:135], v[156:159], v[108:111]
	v_mfma_f32_16x16x32_bf16 v[104:107], v[140:143], v[156:159], v[104:107]
	v_mfma_f32_16x16x32_bf16 v[92:95], v[132:135], v[174:177], v[92:95]
	v_mfma_f32_16x16x32_bf16 v[88:91], v[140:143], v[174:177], v[88:91]
	v_mfma_f32_16x16x32_bf16 v[76:79], v[132:135], v[192:195], v[76:79]
	v_mfma_f32_16x16x32_bf16 v[72:75], v[140:143], v[192:195], v[72:75]
	v_mfma_f32_16x16x32_bf16 v[116:119], v[196:199], v[144:147], v[116:119]
	v_mfma_f32_16x16x32_bf16 v[112:115], v[208:211], v[144:147], v[112:115]
	v_mfma_f32_16x16x32_bf16 v[100:103], v[196:199], v[152:155], v[100:103]
	v_mfma_f32_16x16x32_bf16 v[96:99], v[208:211], v[152:155], v[96:99]
	v_mfma_f32_16x16x32_bf16 v[84:87], v[196:199], v[170:173], v[84:87]
	v_mfma_f32_16x16x32_bf16 v[80:83], v[208:211], v[170:173], v[80:83]
	v_mfma_f32_16x16x32_bf16 v[68:71], v[196:199], v[178:181], v[68:71]
	v_mfma_f32_16x16x32_bf16 v[64:67], v[208:211], v[178:181], v[64:67]
	v_mfma_f32_16x16x32_bf16 v[116:119], v[204:207], v[148:151], v[116:119]
	v_mfma_f32_16x16x32_bf16 v[112:115], v[212:215], v[148:151], v[112:115]
	v_mfma_f32_16x16x32_bf16 v[100:103], v[204:207], v[156:159], v[100:103]
	v_mfma_f32_16x16x32_bf16 v[96:99], v[212:215], v[156:159], v[96:99]
	v_mfma_f32_16x16x32_bf16 v[84:87], v[204:207], v[174:177], v[84:87]
	v_mfma_f32_16x16x32_bf16 v[80:83], v[212:215], v[174:177], v[80:83]
	v_mfma_f32_16x16x32_bf16 v[68:71], v[204:207], v[192:195], v[68:71]
	v_mfma_f32_16x16x32_bf16 v[64:67], v[212:215], v[192:195], v[64:67]
	s_setprio 0
	s_barrier
	ds_read_b128 v[144:147], v187 offset:16384
	ds_read_b128 v[148:151], v187 offset:17408
	ds_read_b128 v[152:155], v187 offset:18432
	ds_read_b128 v[156:159], v187 offset:19456
	ds_read_b128 v[170:173], v187 offset:20480
	ds_read_b128 v[174:177], v187 offset:21504
	ds_read_b128 v[178:181], v187 offset:22528
	ds_read_b128 v[192:195], v187 offset:23552
	s_mov_b32 m0, s40
	v_lshl_add_u64 v[182:183], s[26:27], 0, v[160:161]
	global_load_lds_dwordx4 v[182:183], off
	v_lshl_add_u64 v[200:201], s[26:27], 0, v[162:163]
	s_mov_b32 m0, s41
	s_nop 0
	global_load_lds_dwordx4 v[200:201], off
	s_mov_b32 m0, s42
	v_lshl_add_u64 v[216:217], s[28:29], 0, v[160:161]
	global_load_lds_dwordx4 v[216:217], off
	v_lshl_add_u64 v[218:219], s[28:29], 0, v[162:163]
	s_mov_b32 m0, s43
	s_nop 0
	global_load_lds_dwordx4 v[218:219], off
	s_add_u32 s64, s26, 0x20000
	s_addc_u32 s65, s27, 0
	s_mov_b32 m0, s44
	v_lshl_add_u64 v[248:249], s[64:65], 0, v[160:161]
	global_load_lds_dwordx4 v[248:249], off
	v_lshl_add_u64 v[248:249], s[64:65], 0, v[162:163]
	s_mov_b32 m0, s45
	s_nop 0
	global_load_lds_dwordx4 v[248:249], off
	s_waitcnt lgkmcnt(0)
	s_waitcnt vmcnt(8)
	s_barrier
	s_setprio 1
	v_mfma_f32_16x16x32_bf16 v[60:63], v[128:131], v[144:147], v[60:63]
	v_mfma_f32_16x16x32_bf16 v[56:59], v[136:139], v[144:147], v[56:59]
	v_mfma_f32_16x16x32_bf16 v[44:47], v[128:131], v[152:155], v[44:47]
	v_mfma_f32_16x16x32_bf16 v[40:43], v[136:139], v[152:155], v[40:43]
	v_mfma_f32_16x16x32_bf16 v[28:31], v[128:131], v[170:173], v[28:31]
	v_mfma_f32_16x16x32_bf16 v[24:27], v[136:139], v[170:173], v[24:27]
	v_mfma_f32_16x16x32_bf16 v[12:15], v[128:131], v[178:181], v[12:15]
	v_mfma_f32_16x16x32_bf16 v[8:11], v[136:139], v[178:181], v[8:11]
	v_mfma_f32_16x16x32_bf16 v[60:63], v[132:135], v[148:151], v[60:63]
	v_mfma_f32_16x16x32_bf16 v[56:59], v[140:143], v[148:151], v[56:59]
	v_mfma_f32_16x16x32_bf16 v[44:47], v[132:135], v[156:159], v[44:47]
	v_mfma_f32_16x16x32_bf16 v[40:43], v[140:143], v[156:159], v[40:43]
	v_mfma_f32_16x16x32_bf16 v[28:31], v[132:135], v[174:177], v[28:31]
	v_mfma_f32_16x16x32_bf16 v[24:27], v[140:143], v[174:177], v[24:27]
	v_mfma_f32_16x16x32_bf16 v[12:15], v[132:135], v[192:195], v[12:15]
	v_mfma_f32_16x16x32_bf16 v[8:11], v[140:143], v[192:195], v[8:11]
	v_mfma_f32_16x16x32_bf16 v[52:55], v[196:199], v[144:147], v[52:55]
	v_mfma_f32_16x16x32_bf16 v[48:51], v[208:211], v[144:147], v[48:51]
	v_mfma_f32_16x16x32_bf16 v[36:39], v[196:199], v[152:155], v[36:39]
	v_mfma_f32_16x16x32_bf16 v[32:35], v[208:211], v[152:155], v[32:35]
	v_mfma_f32_16x16x32_bf16 v[20:23], v[196:199], v[170:173], v[20:23]
	v_mfma_f32_16x16x32_bf16 v[16:19], v[208:211], v[170:173], v[16:19]
	v_mfma_f32_16x16x32_bf16 v[4:7], v[196:199], v[178:181], v[4:7]
	v_mfma_f32_16x16x32_bf16 v[0:3], v[208:211], v[178:181], v[0:3]
	v_mfma_f32_16x16x32_bf16 v[52:55], v[204:207], v[148:151], v[52:55]
	v_mfma_f32_16x16x32_bf16 v[48:51], v[212:215], v[148:151], v[48:51]
	v_mfma_f32_16x16x32_bf16 v[36:39], v[204:207], v[156:159], v[36:39]
	v_mfma_f32_16x16x32_bf16 v[32:35], v[212:215], v[156:159], v[32:35]
	v_mfma_f32_16x16x32_bf16 v[20:23], v[204:207], v[174:177], v[20:23]
	v_mfma_f32_16x16x32_bf16 v[16:19], v[212:215], v[174:177], v[16:19]
	v_mfma_f32_16x16x32_bf16 v[4:7], v[204:207], v[192:195], v[4:7]
	v_mfma_f32_16x16x32_bf16 v[0:3], v[212:215], v[192:195], v[0:3]
	s_setprio 0
	s_barrier
	ds_read_b128 v[128:131], v189
	ds_read_b128 v[132:135], v189 offset:1024
	ds_read_b128 v[136:139], v189 offset:2048
	ds_read_b128 v[140:143], v189 offset:3072
	s_add_u32 s28, s28, 0x20000
	s_addc_u32 s29, s29, 0
	s_mov_b32 m0, s46
	v_lshl_add_u64 v[196:197], s[28:29], 0, v[160:161]
	ds_read_b128 v[144:147], v187 offset:32768
	ds_read_b128 v[148:151], v187 offset:33792
	ds_read_b128 v[152:155], v187 offset:34816
	ds_read_b128 v[156:159], v187 offset:35840
	ds_read_b128 v[170:173], v187 offset:36864
	ds_read_b128 v[174:177], v187 offset:37888
	ds_read_b128 v[178:181], v187 offset:38912
	ds_read_b128 v[192:195], v187 offset:39936
	global_load_lds_dwordx4 v[196:197], off
	v_lshl_add_u64 v[196:197], s[28:29], 0, v[162:163]
	s_mov_b32 m0, s47
	s_nop 0
	global_load_lds_dwordx4 v[196:197], off
	ds_read_b128 v[196:199], v190
	ds_read_b128 v[204:207], v190 offset:1024
	ds_read_b128 v[208:211], v190 offset:2048
	ds_read_b128 v[212:215], v190 offset:3072
	s_waitcnt lgkmcnt(0)
	s_waitcnt vmcnt(8)
	s_barrier
	s_setprio 1
	v_mfma_f32_16x16x32_bf16 v[124:127], v[128:131], v[144:147], v[124:127]
	v_mfma_f32_16x16x32_bf16 v[120:123], v[136:139], v[144:147], v[120:123]
	v_mfma_f32_16x16x32_bf16 v[108:111], v[128:131], v[152:155], v[108:111]
	v_mfma_f32_16x16x32_bf16 v[104:107], v[136:139], v[152:155], v[104:107]
	v_mfma_f32_16x16x32_bf16 v[92:95], v[128:131], v[170:173], v[92:95]
	v_mfma_f32_16x16x32_bf16 v[88:91], v[136:139], v[170:173], v[88:91]
	v_mfma_f32_16x16x32_bf16 v[76:79], v[128:131], v[178:181], v[76:79]
	v_mfma_f32_16x16x32_bf16 v[72:75], v[136:139], v[178:181], v[72:75]
	v_mfma_f32_16x16x32_bf16 v[124:127], v[132:135], v[148:151], v[124:127]
	v_mfma_f32_16x16x32_bf16 v[120:123], v[140:143], v[148:151], v[120:123]
	v_mfma_f32_16x16x32_bf16 v[108:111], v[132:135], v[156:159], v[108:111]
	v_mfma_f32_16x16x32_bf16 v[104:107], v[140:143], v[156:159], v[104:107]
	v_mfma_f32_16x16x32_bf16 v[92:95], v[132:135], v[174:177], v[92:95]
	v_mfma_f32_16x16x32_bf16 v[88:91], v[140:143], v[174:177], v[88:91]
	v_mfma_f32_16x16x32_bf16 v[76:79], v[132:135], v[192:195], v[76:79]
	v_mfma_f32_16x16x32_bf16 v[72:75], v[140:143], v[192:195], v[72:75]
	v_mfma_f32_16x16x32_bf16 v[116:119], v[196:199], v[144:147], v[116:119]
	v_mfma_f32_16x16x32_bf16 v[112:115], v[208:211], v[144:147], v[112:115]
	v_mfma_f32_16x16x32_bf16 v[100:103], v[196:199], v[152:155], v[100:103]
	v_mfma_f32_16x16x32_bf16 v[96:99], v[208:211], v[152:155], v[96:99]
	v_mfma_f32_16x16x32_bf16 v[84:87], v[196:199], v[170:173], v[84:87]
	v_mfma_f32_16x16x32_bf16 v[80:83], v[208:211], v[170:173], v[80:83]
	v_mfma_f32_16x16x32_bf16 v[68:71], v[196:199], v[178:181], v[68:71]
	v_mfma_f32_16x16x32_bf16 v[64:67], v[208:211], v[178:181], v[64:67]
	v_mfma_f32_16x16x32_bf16 v[116:119], v[204:207], v[148:151], v[116:119]
	v_mfma_f32_16x16x32_bf16 v[112:115], v[212:215], v[148:151], v[112:115]
	v_mfma_f32_16x16x32_bf16 v[100:103], v[204:207], v[156:159], v[100:103]
	v_mfma_f32_16x16x32_bf16 v[96:99], v[212:215], v[156:159], v[96:99]
	v_mfma_f32_16x16x32_bf16 v[84:87], v[204:207], v[174:177], v[84:87]
	v_mfma_f32_16x16x32_bf16 v[80:83], v[212:215], v[174:177], v[80:83]
	v_mfma_f32_16x16x32_bf16 v[68:71], v[204:207], v[192:195], v[68:71]
	v_mfma_f32_16x16x32_bf16 v[64:67], v[212:215], v[192:195], v[64:67]
	s_setprio 0
	s_barrier
	ds_read_b128 v[144:147], v187 offset:49152
	ds_read_b128 v[148:151], v187 offset:50176
	ds_read_b128 v[152:155], v187 offset:51200
	ds_read_b128 v[156:159], v187 offset:52224
	ds_read_b128 v[170:173], v187 offset:53248
	ds_read_b128 v[174:177], v187 offset:54272
	ds_read_b128 v[178:181], v187 offset:55296
	ds_read_b128 v[192:195], v187 offset:56320
	s_mov_b32 m0, s51
	v_lshl_add_u64 v[182:183], v[182:183], 0, s[10:11]
	global_load_lds_dwordx4 v[182:183], off
	v_lshl_add_u64 v[182:183], v[200:201], 0, s[10:11]
	s_mov_b32 m0, s52
	s_nop 0
	global_load_lds_dwordx4 v[182:183], off
	s_mov_b32 m0, s53
	v_lshl_add_u64 v[182:183], v[216:217], 0, s[10:11]
	global_load_lds_dwordx4 v[182:183], off
	v_lshl_add_u64 v[182:183], v[218:219], 0, s[10:11]
	s_mov_b32 m0, s54
	s_nop 0
	global_load_lds_dwordx4 v[182:183], off
	s_add_u32 s26, s26, 0x20080
	s_addc_u32 s27, s27, 0
	s_mov_b32 m0, s55
	v_lshl_add_u64 v[248:249], s[26:27], 0, v[160:161]
	global_load_lds_dwordx4 v[248:249], off
	v_lshl_add_u64 v[248:249], s[26:27], 0, v[162:163]
	s_mov_b32 m0, s56
	s_nop 0
	global_load_lds_dwordx4 v[248:249], off
	s_waitcnt lgkmcnt(0)
	s_waitcnt vmcnt(8)
	s_barrier
	s_setprio 1
	v_mfma_f32_16x16x32_bf16 v[60:63], v[128:131], v[144:147], v[60:63]
	v_mfma_f32_16x16x32_bf16 v[56:59], v[136:139], v[144:147], v[56:59]
	v_mfma_f32_16x16x32_bf16 v[44:47], v[128:131], v[152:155], v[44:47]
	v_mfma_f32_16x16x32_bf16 v[40:43], v[136:139], v[152:155], v[40:43]
	v_mfma_f32_16x16x32_bf16 v[28:31], v[128:131], v[170:173], v[28:31]
	v_mfma_f32_16x16x32_bf16 v[24:27], v[136:139], v[170:173], v[24:27]
	v_mfma_f32_16x16x32_bf16 v[12:15], v[128:131], v[178:181], v[12:15]
	v_mfma_f32_16x16x32_bf16 v[8:11], v[136:139], v[178:181], v[8:11]
	v_mfma_f32_16x16x32_bf16 v[60:63], v[132:135], v[148:151], v[60:63]
	v_mfma_f32_16x16x32_bf16 v[56:59], v[140:143], v[148:151], v[56:59]
	v_mfma_f32_16x16x32_bf16 v[44:47], v[132:135], v[156:159], v[44:47]
	v_mfma_f32_16x16x32_bf16 v[40:43], v[140:143], v[156:159], v[40:43]
	v_mfma_f32_16x16x32_bf16 v[28:31], v[132:135], v[174:177], v[28:31]
	v_mfma_f32_16x16x32_bf16 v[24:27], v[140:143], v[174:177], v[24:27]
	v_mfma_f32_16x16x32_bf16 v[12:15], v[132:135], v[192:195], v[12:15]
	v_mfma_f32_16x16x32_bf16 v[8:11], v[140:143], v[192:195], v[8:11]
	v_mfma_f32_16x16x32_bf16 v[52:55], v[196:199], v[144:147], v[52:55]
	v_mfma_f32_16x16x32_bf16 v[48:51], v[208:211], v[144:147], v[48:51]
	v_mfma_f32_16x16x32_bf16 v[36:39], v[196:199], v[152:155], v[36:39]
	v_mfma_f32_16x16x32_bf16 v[32:35], v[208:211], v[152:155], v[32:35]
	v_mfma_f32_16x16x32_bf16 v[20:23], v[196:199], v[170:173], v[20:23]
	v_mfma_f32_16x16x32_bf16 v[16:19], v[208:211], v[170:173], v[16:19]
	v_mfma_f32_16x16x32_bf16 v[4:7], v[196:199], v[178:181], v[4:7]
	v_mfma_f32_16x16x32_bf16 v[0:3], v[208:211], v[178:181], v[0:3]
	v_mfma_f32_16x16x32_bf16 v[52:55], v[204:207], v[148:151], v[52:55]
	v_mfma_f32_16x16x32_bf16 v[48:51], v[212:215], v[148:151], v[48:51]
	v_mfma_f32_16x16x32_bf16 v[36:39], v[204:207], v[156:159], v[36:39]
	v_mfma_f32_16x16x32_bf16 v[32:35], v[212:215], v[156:159], v[32:35]
	v_mfma_f32_16x16x32_bf16 v[20:23], v[204:207], v[174:177], v[20:23]
	v_mfma_f32_16x16x32_bf16 v[16:19], v[212:215], v[174:177], v[16:19]
	v_mfma_f32_16x16x32_bf16 v[4:7], v[204:207], v[192:195], v[4:7]
	v_mfma_f32_16x16x32_bf16 v[0:3], v[212:215], v[192:195], v[0:3]
	s_setprio 0
	s_add_i32 s38, s38, 2
	s_add_u32 s24, s24, 0x100
	s_addc_u32 s25, s25, 0
	s_add_u32 s36, s36, 0x100
	s_addc_u32 s37, s37, 0
	s_cmp_gt_u32 s38, 5
	s_barrier
	s_cbranch_scc0 .LBB0_1128
	s_and_b64 vcc, exec, s[16:17]
	s_cbranch_vccnz .Lp8_noA
	s_add_u32 s80, s12, 0x20080
	s_addc_u32 s81, s13, 0
	v_lshl_add_u64 v[182:183], s[80:81], 0, v[164:165]
	s_add_i32 m0, s42, 0xc000
	s_nop 0
	global_load_lds_dwordx4 v[182:183], off
	v_lshl_add_u64 v[182:183], s[80:81], 0, v[166:167]
	s_add_i32 m0, s42, 0xe000
	s_nop 0
	global_load_lds_dwordx4 v[182:183], off
.Lp8_noA:
	v_lshl_or_b32 v128, s63, 8, v185
	v_lshl_add_u32 v170, s18, 8, v184
	v_ashrrev_i32_e32 v129, 31, v128
	v_lshlrev_b64 v[174:175], 1, v[128:129]
	v_ashrrev_i32_e32 v171, 31, v170
	v_lshl_add_u64 v[128:129], s[8:9], 0, v[174:175]
	v_lshlrev_b64 v[204:205], 11, v[170:171]
	v_lshl_add_u64 v[130:131], v[128:129], 0, v[204:205]
	v_mov_b32_e32 v194, v220
	v_mov_b32_e32 v195, v221
	v_mov_b32_e32 v196, v222
	v_mov_b32_e32 v197, v223
	v_mov_b32_e32 v198, v224
	v_mov_b32_e32 v199, v225
	v_mov_b32_e32 v200, v226
	v_mov_b32_e32 v201, v227
	v_or_b32_e32 v130, 16, v170
	v_or_b32_e32 v132, 32, v170
	v_or_b32_e32 v134, 48, v170
	v_ashrrev_i32_e32 v131, 31, v130
	v_ashrrev_i32_e32 v133, 31, v132
	v_ashrrev_i32_e32 v135, 31, v134
	v_lshlrev_b64 v[182:183], 11, v[130:131]
	v_add_u32_e32 v178, 0x80, v170
	v_lshlrev_b64 v[180:181], 11, v[132:133]
	v_lshlrev_b64 v[176:177], 11, v[134:135]
	v_lshl_add_u64 v[132:133], v[128:129], 0, v[182:183]
	v_ashrrev_i32_e32 v179, 31, v178
	v_lshl_add_u64 v[134:135], v[128:129], 0, v[180:181]
	v_lshl_add_u64 v[128:129], v[128:129], 0, v[176:177]
	v_mov_b32_e32 v156, v228
	v_mov_b32_e32 v157, v229
	v_mov_b32_e32 v158, v230
	v_mov_b32_e32 v159, v231
	v_mov_b32_e32 v152, v232
	v_mov_b32_e32 v153, v233
	v_mov_b32_e32 v154, v234
	v_mov_b32_e32 v155, v235
	v_mov_b32_e32 v148, v236
	v_mov_b32_e32 v149, v237
	v_mov_b32_e32 v150, v238
	v_mov_b32_e32 v151, v239
	v_mov_b32_e32 v144, v240
	v_mov_b32_e32 v145, v241
	v_mov_b32_e32 v146, v242
	v_mov_b32_e32 v147, v243
	v_mov_b32_e32 v140, v252
	v_mov_b32_e32 v141, v253
	v_mov_b32_e32 v142, v254
	v_mov_b32_e32 v143, v255
	global_load_dwordx4 v[136:139], v[128:129], off offset:64
	v_lshlrev_b64 v[130:131], 11, v[178:179]
	v_lshl_add_u64 v[130:131], s[8:9], 0, v[130:131]
	v_lshl_add_u64 v[172:173], v[130:131], 0, v[174:175]
	global_load_dwordx4 v[132:135], v[172:173], off
	global_load_dwordx4 v[128:131], v[172:173], off offset:64
	v_and_b32_e32 v192, 64, v191
	v_xor_b32_e32 v179, 16, v191
	v_add_u32_e32 v192, 64, v192
	v_xor_b32_e32 v193, 32, v191
	v_cmp_lt_i32_e32 vcc, v179, v192
	v_lshl_add_u64 v[204:205], s[8:9], 0, v[204:205]
	v_lshl_add_u64 v[204:205], v[204:205], 0, v[174:175]
	v_cndmask_b32_e32 v179, v191, v179, vcc
	v_cmp_lt_i32_e32 vcc, v193, v192
	v_lshlrev_b32_e32 v192, 2, v179
	s_lshl_b32 s18, s63, 2
	v_cndmask_b32_e32 v193, v191, v193, vcc
	v_lshlrev_b32_e32 v179, 2, v193
	s_or_b32 s25, s18, s50
	s_mul_hi_i32 s24, s25, 0x21000
	s_mul_i32 s25, s25, 0x21000
	v_lshlrev_b32_e32 v206, 16, v194
	v_and_b32_e32 v207, 0xffff0000, v194
	v_lshlrev_b32_e32 v194, 16, v195
	v_and_b32_e32 v195, 0xffff0000, v195
	v_lshlrev_b32_e32 v208, 16, v196
	v_and_b32_e32 v209, 0xffff0000, v196
	v_lshlrev_b32_e32 v196, 16, v197
	v_and_b32_e32 v197, 0xffff0000, v197
	v_lshlrev_b32_e32 v212, 16, v200
	v_and_b32_e32 v213, 0xffff0000, v200
	v_lshlrev_b32_e32 v200, 16, v201
	v_and_b32_e32 v201, 0xffff0000, v201
	v_pk_add_f32 v[126:127], v[126:127], v[194:195]
	v_pk_add_f32 v[124:125], v[124:125], v[206:207]
	v_pk_add_f32 v[122:123], v[122:123], v[196:197]
	v_pk_add_f32 v[120:121], v[120:121], v[208:209]
	v_lshlrev_b32_e32 v210, 16, v198
	v_and_b32_e32 v211, 0xffff0000, v198
	v_lshlrev_b32_e32 v198, 16, v199
	v_and_b32_e32 v199, 0xffff0000, v199
	v_pk_add_f32 v[194:195], v[114:115], v[200:201]
	v_pk_add_f32 v[196:197], v[112:113], v[212:213]
	v_cvt_pk_bf16_f32 v112, v124, v125
	v_cvt_pk_bf16_f32 v113, v126, v127
	v_mul_f32_e32 v114, v125, v125
	v_mul_f32_e32 v115, v127, v127
	v_mul_f32_e32 v125, v121, v121
	v_mul_f32_e32 v127, v123, v123
	v_pk_add_f32 v[118:119], v[118:119], v[198:199]
	v_pk_add_f32 v[116:117], v[116:117], v[210:211]
	v_fmac_f32_e32 v114, v124, v124
	v_fmac_f32_e32 v115, v126, v126
	v_fmac_f32_e32 v125, v120, v120
	v_fmac_f32_e32 v127, v122, v122
	v_mul_f32_e32 v193, v117, v117
	v_mul_f32_e32 v198, v119, v119
	v_add_f32_e32 v114, v114, v115
	v_add_f32_e32 v115, v125, v127
	v_mul_f32_e32 v124, v197, v197
	v_mul_f32_e32 v125, v195, v195
	v_fmac_f32_e32 v193, v116, v116
	v_fmac_f32_e32 v198, v118, v118
	v_fmac_f32_e32 v124, v196, v196
	v_fmac_f32_e32 v125, v194, v194
	v_add_f32_e32 v114, v114, v115
	v_add_f32_e32 v115, v193, v198
	v_add_f32_e32 v124, v124, v125
	v_add_f32_e32 v115, v115, v124
	v_add_f32_e32 v124, v114, v115
	ds_bpermute_b32 v125, v192, v124
	v_cvt_pk_bf16_f32 v114, v120, v121
	v_cvt_pk_bf16_f32 v115, v122, v123
	global_store_dwordx4 v[204:205], v[112:115], off
	s_waitcnt lgkmcnt(0)
	s_nop 0
	v_add_f32_e32 v112, v124, v125
	ds_bpermute_b32 v113, v179, v112
	v_cvt_pk_bf16_f32 v114, v116, v117
	v_cvt_pk_bf16_f32 v115, v118, v119
	v_cvt_pk_bf16_f32 v116, v196, v197
	v_cvt_pk_bf16_f32 v117, v194, v195
	global_store_dwordx4 v[204:205], v[114:117], off offset:64
	s_and_saveexec_b64 s[18:19], s[4:5]
	s_cbranch_execz .LBB0_1131
	s_add_u32 s26, s48, s25
	s_addc_u32 s27, s49, s24
	s_waitcnt lgkmcnt(0)
	v_add_f32_e32 v114, v112, v113
	v_lshl_add_u64 v[112:113], v[170:171], 2, s[26:27]
	global_store_dword v[112:113], v114, off
